# experiment on combo: non-temporal (nt) hint on the mixer chains' streamed input loads
# baseline (speedup 1.0000x reference)
.LBB0_343:
	s_bfe_u32 s36, s65, 0x20006
	s_and_b32 s0, s65, 63
	s_waitcnt vmcnt(0)
	v_mov_b32_e32 v68, v186
	v_writelane_b32 v255, s0, 33
	s_cmp_lt_i32 s36, 2
	s_mov_b64 s[4:5], -1
	s_cbranch_scc1 .LBB0_454
	s_cmp_gt_i32 s36, 2
	s_cbranch_scc0 .LBB0_398
	v_readfirstlane_b32 s0, v68
	v_readlane_b32 s4, v255, 33
	s_ashr_i32 s0, s0, 6
	s_lshl_b32 s4, s4, 2
	s_and_b32 s1, s0, 3
	s_and_b32 s4, s4, 12
	s_bfe_u32 s2, s65, 0x10002
	s_or_b32 s14, s1, s4
	s_cmp_gt_i32 s0, 3
	s_cselect_b64 s[8:9], -1, 0
	s_lshl_b32 s0, s2, 4
	v_readlane_b32 s4, v255, 28
	s_or_b32 s0, s0, s4
	s_or_b32 s0, s14, s0
	s_mul_hi_i32 s4, s0, 0x2200
	s_mulk_i32 s0, 0x2200
	v_readlane_b32 s5, v255, 31
	s_add_u32 s10, s5, s0
	v_readlane_b32 s0, v255, 32
	v_and_b32_e32 v69, 63, v68
	s_addc_u32 s11, s0, s4
	s_mov_b64 s[4:5], -1
	s_and_b64 vcc, exec, s[8:9]
	s_cbranch_vccz .LBB0_347
	v_mul_u32_u24_e32 v4, 34, v69
	v_lshlrev_b32_e32 v4, 2, v4
	global_load_dwordx2 v[70:71], v4, s[10:11] nt
	s_mov_b64 s[4:5], 0
.LBB0_347:
	v_bfe_u32 v73, v68, 4, 2
	v_and_b32_e32 v72, 15, v68
	s_andn2_b64 vcc, exec, s[4:5]
	v_cmp_gt_u32_e64 s[6:7], 32, v69
	v_lshlrev_b32_e32 v75, 3, v73
	s_cbranch_vccnz .LBB0_365
	v_mul_u32_u24_e32 v5, 34, v72
	v_mov_b32_e32 v4, 0
	v_lshlrev_b32_e32 v180, 2, v5
	v_lshlrev_b32_e32 v36, 2, v75
	v_mov_b32_e32 v8, 0
	v_mov_b32_e32 v9, 0
	v_mov_b32_e32 v10, 0
	v_mov_b32_e32 v11, 0
	s_and_saveexec_b64 s[4:5], s[6:7]
	s_cbranch_execz .LBB0_350
	v_lshl_add_u64 v[6:7], s[10:11], 0, v[180:181]
	v_mov_b32_e32 v37, v181
	v_lshl_add_u64 v[6:7], v[6:7], 0, v[36:37]
	global_load_dwordx4 v[8:11], v[6:7], off offset:8 nt
	global_load_dwordx4 v[12:15], v[6:7], off offset:24 nt
	s_waitcnt vmcnt(1)
	v_cvt_pk_bf16_f32 v8, v8, v9
	v_cvt_pk_bf16_f32 v9, v10, v11
	s_waitcnt vmcnt(0)
	v_cvt_pk_bf16_f32 v10, v12, v13
	v_cvt_pk_bf16_f32 v11, v14, v15
.LBB0_350:
	s_or_b64 exec, exec, s[4:5]
	v_mov_b32_e32 v5, 0
	v_mov_b32_e32 v6, 0
	v_mov_b32_e32 v7, 0
	s_and_saveexec_b64 s[4:5], s[6:7]
	s_cbranch_execz .LBB0_352
	v_lshl_add_u64 v[4:5], s[10:11], 0, v[180:181]
	v_mov_b32_e32 v37, v181
	v_lshl_add_u64 v[12:13], v[4:5], 0, v[36:37]
	global_load_dwordx4 v[4:7], v[12:13], off offset:2184 nt
	s_nop 0
	global_load_dwordx4 v[12:15], v[12:13], off offset:2200 nt
	s_waitcnt vmcnt(1)
	v_cvt_pk_bf16_f32 v4, v4, v5
	v_cvt_pk_bf16_f32 v5, v6, v7
	s_waitcnt vmcnt(0)
	v_cvt_pk_bf16_f32 v6, v12, v13
	v_cvt_pk_bf16_f32 v7, v14, v15
.LBB0_352:
	s_or_b64 exec, exec, s[4:5]
	v_mov_b32_e32 v12, 0
	v_mov_b32_e32 v16, 0
	v_mov_b32_e32 v17, 0
	v_mov_b32_e32 v18, 0
	v_mov_b32_e32 v19, 0
	s_waitcnt lgkmcnt(0)
	s_and_saveexec_b64 s[12:13], s[6:7]
	s_cbranch_execz .LBB0_354
	v_lshl_add_u64 v[14:15], s[10:11], 0, v[180:181]
	v_mov_b32_e32 v37, v181
	v_lshl_add_u64 v[14:15], v[14:15], 0, v[36:37]
	v_add_co_u32_e32 v16, vcc, 0x1000, v14
	s_mov_b64 s[4:5], 0x1108
	s_nop 0
	v_addc_co_u32_e32 v17, vcc, 0, v15, vcc
	v_lshl_add_u64 v[14:15], v[14:15], 0, s[4:5]
	global_load_dwordx4 v[16:19], v[16:17], off offset:264 nt
	s_nop 0
	global_load_dwordx4 v[20:23], v[14:15], off offset:16 nt
	s_waitcnt vmcnt(1)
	v_cvt_pk_bf16_f32 v16, v16, v17
	v_cvt_pk_bf16_f32 v17, v18, v19
	s_waitcnt vmcnt(0)
	v_cvt_pk_bf16_f32 v18, v20, v21
	v_cvt_pk_bf16_f32 v19, v22, v23
.LBB0_354:
	s_or_b64 exec, exec, s[12:13]
	v_mov_b32_e32 v13, 0
	v_mov_b32_e32 v14, 0
	v_mov_b32_e32 v15, 0
	s_and_saveexec_b64 s[12:13], s[6:7]
	s_cbranch_execz .LBB0_356
	v_lshl_add_u64 v[12:13], s[10:11], 0, v[180:181]
	v_mov_b32_e32 v37, v181
	v_lshl_add_u64 v[20:21], v[12:13], 0, v[36:37]
	v_add_co_u32_e32 v12, vcc, 0x1000, v20
	s_mov_b64 s[4:5], 0x1988
	s_nop 0
	v_addc_co_u32_e32 v13, vcc, 0, v21, vcc
	v_lshl_add_u64 v[20:21], v[20:21], 0, s[4:5]
	global_load_dwordx4 v[12:15], v[12:13], off offset:2440 nt
	s_nop 0
	global_load_dwordx4 v[20:23], v[20:21], off offset:16 nt
	s_waitcnt vmcnt(1)
	v_cvt_pk_bf16_f32 v12, v12, v13
	v_cvt_pk_bf16_f32 v13, v14, v15
	s_waitcnt vmcnt(0)
	v_cvt_pk_bf16_f32 v14, v20, v21
	v_cvt_pk_bf16_f32 v15, v22, v23
.LBB0_356:
	s_or_b64 exec, exec, s[12:13]
	v_mov_b32_e32 v20, 0
	v_mov_b32_e32 v24, 0
	v_mov_b32_e32 v25, 0
	v_mov_b32_e32 v26, 0
	v_mov_b32_e32 v27, 0
	s_and_saveexec_b64 s[4:5], s[6:7]
	s_cbranch_execz .LBB0_358
	v_lshl_add_u64 v[22:23], s[10:11], 0, v[180:181]
	v_mov_b32_e32 v37, v181
	v_lshl_add_u64 v[22:23], v[22:23], 0, v[36:37]
	global_load_dwordx4 v[24:27], v[22:23], off offset:72 nt
	global_load_dwordx4 v[28:31], v[22:23], off offset:88 nt
	s_waitcnt vmcnt(1)
	v_cvt_pk_bf16_f32 v24, v24, v25
	v_cvt_pk_bf16_f32 v25, v26, v27
	s_waitcnt vmcnt(0)
	v_cvt_pk_bf16_f32 v26, v28, v29
	v_cvt_pk_bf16_f32 v27, v30, v31
.LBB0_358:
	s_or_b64 exec, exec, s[4:5]
	v_mov_b32_e32 v21, 0
	v_mov_b32_e32 v22, 0
	v_mov_b32_e32 v23, 0
	s_and_saveexec_b64 s[4:5], s[6:7]
	s_cbranch_execz .LBB0_360
	v_lshl_add_u64 v[20:21], s[10:11], 0, v[180:181]
	v_mov_b32_e32 v37, v181
	v_lshl_add_u64 v[28:29], v[20:21], 0, v[36:37]
	global_load_dwordx4 v[20:23], v[28:29], off offset:2248 nt
	s_nop 0
	global_load_dwordx4 v[28:31], v[28:29], off offset:2264 nt
	s_waitcnt vmcnt(1)
	v_cvt_pk_bf16_f32 v20, v20, v21
	v_cvt_pk_bf16_f32 v21, v22, v23
	s_waitcnt vmcnt(0)
	v_cvt_pk_bf16_f32 v22, v28, v29
	v_cvt_pk_bf16_f32 v23, v30, v31
.LBB0_360:
	s_or_b64 exec, exec, s[4:5]
	v_mov_b32_e32 v28, 0
	v_mov_b32_e32 v32, 0
	v_mov_b32_e32 v33, 0
	v_mov_b32_e32 v34, 0
	v_mov_b32_e32 v35, 0
	s_and_saveexec_b64 s[12:13], s[6:7]
	s_cbranch_execz .LBB0_362
	v_lshl_add_u64 v[30:31], s[10:11], 0, v[180:181]
	v_mov_b32_e32 v37, v181
	v_lshl_add_u64 v[30:31], v[30:31], 0, v[36:37]
	v_add_co_u32_e32 v32, vcc, 0x1000, v30
	s_mov_b64 s[4:5], 0x1148
	s_nop 0
	v_addc_co_u32_e32 v33, vcc, 0, v31, vcc
	v_lshl_add_u64 v[30:31], v[30:31], 0, s[4:5]
	global_load_dwordx4 v[32:35], v[32:33], off offset:328 nt
	s_nop 0
	global_load_dwordx4 v[38:41], v[30:31], off offset:16 nt
	s_waitcnt vmcnt(1)
	v_cvt_pk_bf16_f32 v32, v32, v33
	v_cvt_pk_bf16_f32 v33, v34, v35
	s_waitcnt vmcnt(0)
	v_cvt_pk_bf16_f32 v34, v38, v39
	v_cvt_pk_bf16_f32 v35, v40, v41
.LBB0_362:
	s_or_b64 exec, exec, s[12:13]
	v_mov_b32_e32 v29, 0
	v_mov_b32_e32 v30, 0
	v_mov_b32_e32 v31, 0
	s_and_saveexec_b64 s[12:13], s[6:7]
	s_cbranch_execz .LBB0_364
	v_lshl_add_u64 v[28:29], s[10:11], 0, v[180:181]
	v_mov_b32_e32 v37, v181
	v_lshl_add_u64 v[36:37], v[28:29], 0, v[36:37]
	v_add_co_u32_e32 v28, vcc, 0x1000, v36
	s_mov_b64 s[4:5], 0x19c8
	s_nop 0
	v_addc_co_u32_e32 v29, vcc, 0, v37, vcc
	v_lshl_add_u64 v[36:37], v[36:37], 0, s[4:5]
	global_load_dwordx4 v[28:31], v[28:29], off offset:2504 nt
	s_nop 0
	global_load_dwordx4 v[36:39], v[36:37], off offset:16 nt
	s_waitcnt vmcnt(1)
	v_cvt_pk_bf16_f32 v28, v28, v29
	v_cvt_pk_bf16_f32 v29, v30, v31
	s_waitcnt vmcnt(0)
	v_cvt_pk_bf16_f32 v30, v36, v37
	v_cvt_pk_bf16_f32 v31, v38, v39
.LBB0_364:
	s_or_b64 exec, exec, s[12:13]
	s_load_dwordx4 s[4:7], s[80:81], 0xa8
	v_readlane_b32 s0, v255, 29
	s_or_b32 s10, s14, s0
	s_ashr_i32 s11, s10, 31
	s_lshl_b64 s[10:11], s[10:11], 12
	v_lshl_or_b32 v36, v72, 8, s10
	v_mov_b32_e32 v37, s11
	s_waitcnt lgkmcnt(0)
	v_lshl_add_u64 v[38:39], s[4:5], 0, v[36:37]
	v_lshlrev_b32_e32 v180, 4, v73
	v_lshl_add_u64 v[36:37], s[6:7], 0, v[36:37]
	v_lshl_add_u64 v[52:53], v[38:39], 0, v[180:181]
	v_lshl_add_u64 v[54:55], v[36:37], 0, v[180:181]
	global_load_dwordx4 v[36:39], v[52:53], off nt
	global_load_dwordx4 v[40:43], v[54:55], off nt
	s_waitcnt vmcnt(2)
	v_mov_b32_e32 v71, 0
	v_mov_b32_e32 v70, 0
	s_waitcnt vmcnt(0)
	v_xor_b32_e32 v40, 0x80000000, v40
	v_cvt_pk_bf16_f32 v36, v36, v40
	v_xor_b32_e32 v40, 0x80000000, v41
	v_cvt_pk_bf16_f32 v37, v37, v40
	v_xor_b32_e32 v40, 0x80000000, v42
	v_cvt_pk_bf16_f32 v38, v38, v40
	v_xor_b32_e32 v40, 0x80000000, v43
	v_cvt_pk_bf16_f32 v39, v39, v40
	global_load_dwordx4 v[40:43], v[52:53], off offset:64 nt
	global_load_dwordx4 v[44:47], v[54:55], off offset:64 nt
	s_waitcnt vmcnt(0)
	v_xor_b32_e32 v44, 0x80000000, v44
	v_cvt_pk_bf16_f32 v40, v40, v44
	v_xor_b32_e32 v44, 0x80000000, v45
	v_cvt_pk_bf16_f32 v41, v41, v44
	v_xor_b32_e32 v44, 0x80000000, v46
	v_cvt_pk_bf16_f32 v42, v42, v44
	v_xor_b32_e32 v44, 0x80000000, v47
	v_cvt_pk_bf16_f32 v43, v43, v44
	global_load_dwordx4 v[44:47], v[52:53], off offset:128 nt
	global_load_dwordx4 v[48:51], v[54:55], off offset:128 nt
	s_waitcnt vmcnt(0)
	v_xor_b32_e32 v48, 0x80000000, v48
	v_cvt_pk_bf16_f32 v44, v44, v48
	v_xor_b32_e32 v48, 0x80000000, v49
	v_cvt_pk_bf16_f32 v45, v45, v48
	v_xor_b32_e32 v48, 0x80000000, v50
	v_cvt_pk_bf16_f32 v46, v46, v48
	v_xor_b32_e32 v48, 0x80000000, v51
	v_cvt_pk_bf16_f32 v47, v47, v48
	global_load_dwordx4 v[48:51], v[52:53], off offset:192 nt
	s_nop 0
	global_load_dwordx4 v[52:55], v[54:55], off offset:192 nt
	s_waitcnt vmcnt(0)
	v_xor_b32_e32 v52, 0x80000000, v52
	v_cvt_pk_bf16_f32 v48, v48, v52
	v_xor_b32_e32 v52, 0x80000000, v53
	v_cvt_pk_bf16_f32 v49, v49, v52
	v_xor_b32_e32 v52, 0x80000000, v54
	v_cvt_pk_bf16_f32 v50, v50, v52
	v_xor_b32_e32 v52, 0x80000000, v55
	v_cvt_pk_bf16_f32 v51, v51, v52
	s_branch .LBB0_366

.LBB0_366:
	v_readlane_b32 s0, v255, 33
	s_lshr_b32 s0, s0, 3
	s_cmp_eq_u32 s2, 0
	v_sub_u32_e32 v52, 0, v72
	s_cselect_b64 s[6:7], -1, 0
	s_mulk_i32 s1, 0x7600
	s_add_i32 s1, s1, 0
	s_andn2_b64 vcc, exec, s[8:9]
	v_cndmask_b32_e64 v74, v52, v72, s[6:7]
	s_cbranch_vccnz .LBB0_370
	s_lshl_b32 s2, s0, 8
	s_and_b64 s[4:5], s[6:7], exec
	s_cselect_b32 s4, 0, 0xff
	s_or_b32 s11, s4, s2
	s_lshl_b32 s10, s14, 4
	v_cmp_gt_u32_e32 vcc, 32, v69
	s_and_saveexec_b64 s[4:5], vcc
	s_cbranch_execz .LBB0_369
	v_add_u32_e32 v52, s11, v74
	v_mul_u32_u24_e32 v52, 0xe00, v52
	v_or_b32_e32 v52, s10, v52
	s_movk_i32 s11, 0xd00
	v_add3_u32 v52, v52, v75, s11
	v_ashrrev_i32_e32 v53, 31, v52
	v_lshl_add_u64 v[52:53], v[52:53], 1, s[82:83]
	global_load_dwordx4 v[52:55], v[52:53], off nt
	v_lshlrev_b32_e32 v56, 5, v72
	v_and_b32_e32 v57, 48, v68
	v_add3_u32 v56, s1, v56, v57
	s_waitcnt vmcnt(0)
	ds_write_b128 v56, v[52:55] offset:29184
.LBB0_369:
	s_or_b64 exec, exec, s[4:5]
	s_and_b64 s[4:5], s[6:7], exec
	s_cselect_b32 s4, 16, 0xef
	s_or_b32 s4, s4, s2
	v_add_u32_e32 v52, s4, v74
	s_and_b64 s[4:5], s[6:7], exec
	s_cselect_b32 s4, 32, 0xdf
	s_or_b32 s4, s4, s2
	v_add_u32_e32 v54, s4, v74
	s_and_b64 s[4:5], s[6:7], exec
	s_cselect_b32 s4, 48, 0xcf
	s_or_b32 s4, s4, s2
	v_add_u32_e32 v60, s4, v74
	s_and_b64 s[4:5], s[6:7], exec
	s_cselect_b32 s4, 64, 0xbf
	s_or_b32 s2, s4, s2
	v_add_u32_e32 v63, s2, v74
	v_mul_u32_u24_e32 v52, 0xe00, v52
	v_mul_u32_u24_e32 v54, 0xe00, v54
	v_mul_u32_u24_e32 v60, 0xe00, v60
	v_mul_u32_u24_e32 v63, 0xe00, v63
	v_and_b32_e32 v62, 8, v75
	v_or_b32_e32 v52, s10, v52
	s_movk_i32 s11, 0xd00
	v_or_b32_e32 v54, s10, v54
	v_or_b32_e32 v60, s10, v60
	v_or_b32_e32 v63, s10, v63
	v_add3_u32 v52, v52, v62, s11
	v_add3_u32 v54, v54, v62, s11
	v_add3_u32 v60, v60, v62, s11
	v_add3_u32 v62, v63, v62, s11
	v_ashrrev_i32_e32 v53, 31, v52
	v_ashrrev_i32_e32 v55, 31, v54
	v_ashrrev_i32_e32 v61, 31, v60
	v_ashrrev_i32_e32 v63, 31, v62
	v_lshl_add_u64 v[52:53], v[52:53], 1, s[82:83]
	v_lshl_add_u64 v[56:57], v[54:55], 1, s[82:83]
	v_lshl_add_u64 v[60:61], v[60:61], 1, s[82:83]
	v_lshl_add_u64 v[62:63], v[62:63], 1, s[82:83]
	global_load_dwordx4 v[52:55], v[52:53], off nt
	s_nop 0
	global_load_dwordx4 v[56:59], v[56:57], off nt
	s_nop 0
	global_load_dwordx4 v[64:67], v[60:61], off nt
	s_nop 0
	global_load_dwordx4 v[60:63], v[62:63], off nt

.LBB0_372:
	s_or_b64 exec, exec, s[4:5]
	s_min_u32 s4, s10, 0x10a
	s_lshl_b32 s4, s4, 4
	s_cmp_lt_u32 s10, 11
	s_movk_i32 s5, 0xff50
	s_movk_i32 s10, 0xaf
	s_cselect_b32 s5, 0x50, s5
	s_cselect_b32 s10, s10, 0x10af
	s_cselect_b32 s11, s8, s2
	s_add_i32 s12, s4, s5
	s_sub_i32 s10, s10, s4
	s_and_b64 s[4:5], s[6:7], exec
	s_cselect_b32 s4, s12, s10
	s_add_i32 s4, s4, s11
	v_add_u32_e32 v60, s4, v74
	v_mad_u32_u24 v60, v60, s63, v82
	v_ashrrev_i32_e32 v61, 31, v60
	v_lshl_add_u64 v[60:61], v[60:61], 1, s[82:83]
	global_load_dwordx4 v[60:63], v[60:61], off nt

.LBB0_376:
	s_or_b64 exec, exec, s[4:5]
	s_add_i32 s9, s10, 4
	s_min_u32 s4, s9, 0x10a
	s_lshl_b32 s4, s4, 4
	s_cmp_lt_u32 s9, 11
	s_movk_i32 s5, 0xff50
	s_movk_i32 s11, 0xaf
	s_cselect_b32 s5, 0x50, s5
	s_cselect_b32 s11, s11, 0x10af
	s_cselect_b32 s12, s8, s2
	s_add_i32 s13, s4, s5
	s_sub_i32 s11, s11, s4
	s_and_b64 s[4:5], s[6:7], exec
	s_cselect_b32 s4, s13, s11
	s_add_i32 s4, s4, s12
	s_waitcnt vmcnt(3)
	v_add_u32_e32 v52, s4, v74
	v_mad_u32_u24 v52, v52, s63, v82
	v_ashrrev_i32_e32 v53, 31, v52
	v_lshl_add_u64 v[52:53], v[52:53], 1, s[82:83]
	global_load_dwordx4 v[52:55], v[52:53], off nt
	s_add_i32 s4, s10, 3
	s_cmpk_gt_u32 s4, 0x10f
	v_xor_b32_e32 v75, 0x80000000, v71
	v_add_u32_e32 v88, 0x6000, v87
	v_add_u32_e32 v86, 0x6200, v87
	v_add_u32_e32 v81, 0x6400, v87
	v_add_u32_e32 v80, 0x6600, v87
	v_add_u32_e32 v79, 0x6800, v87
	v_add_u32_e32 v78, 0x6a00, v87
	v_add_u32_e32 v77, 0x6c00, v87
	v_add_u32_e32 v76, 0x6e00, v87
	s_cbranch_scc1 .LBB0_378
	ds_read_b128 v[92:95], v83 offset:15360
	ds_read_b128 v[96:99], v83 offset:15376
	ds_read_b128 v[100:103], v83 offset:10240
	ds_read_b128 v[104:107], v83 offset:10256
	ds_read_b128 v[108:111], v83 offset:10272
	ds_read_b128 v[112:115], v83 offset:10288
	ds_read_b128 v[116:119], v83 offset:15392
	ds_read_b128 v[120:123], v83 offset:15408
	s_waitcnt lgkmcnt(7)
	v_fma_f32 v92, v71, v89, v92
	s_waitcnt lgkmcnt(5)
	v_fma_f32 v91, v75, v90, v100
	s_waitcnt lgkmcnt(0)
	v_fma_f32 v89, v70, v89, v91
	v_fma_f32 v90, v70, v90, v92
	v_fma_f32 v92, v75, v90, v101
	v_cvt_pk_bf16_f32 v91, v89, v90
	v_fma_f32 v93, v71, v89, v93
	v_fma_f32 v89, v70, v89, v92
	v_fma_f32 v90, v70, v90, v93
	v_cvt_pk_bf16_f32 v92, v89, v90
	ds_write2_b32 v88, v91, v92 offset0:64 offset1:132
	v_fma_f32 v92, v71, v89, v94
	v_fma_f32 v91, v75, v90, v102
	v_fma_f32 v89, v70, v89, v91
	v_fma_f32 v90, v70, v90, v92
	v_fma_f32 v92, v75, v90, v103
	v_cvt_pk_bf16_f32 v91, v89, v90
	v_fma_f32 v93, v71, v89, v95
	v_fma_f32 v89, v70, v89, v92
	v_fma_f32 v90, v70, v90, v93
	v_cvt_pk_bf16_f32 v92, v89, v90
	ds_write2_b32 v86, v91, v92 offset0:72 offset1:140
	v_fma_f32 v92, v71, v89, v96
	s_waitcnt lgkmcnt(6)
	v_fma_f32 v91, v75, v90, v104
	v_fma_f32 v89, v70, v89, v91
	v_fma_f32 v90, v70, v90, v92
	v_fma_f32 v92, v75, v90, v105
	v_cvt_pk_bf16_f32 v91, v89, v90
	v_fma_f32 v93, v71, v89, v97
	v_fma_f32 v89, v70, v89, v92
	v_fma_f32 v90, v70, v90, v93
	v_cvt_pk_bf16_f32 v92, v89, v90
	ds_write2_b32 v81, v91, v92 offset0:80 offset1:148
	v_fma_f32 v92, v71, v89, v98
	v_fma_f32 v91, v75, v90, v106
	v_fma_f32 v89, v70, v89, v91
	v_fma_f32 v90, v70, v90, v92
	v_fma_f32 v92, v75, v90, v107
	v_cvt_pk_bf16_f32 v91, v89, v90
	v_fma_f32 v93, v71, v89, v99
	v_fma_f32 v89, v70, v89, v92
	v_fma_f32 v90, v70, v90, v93
	v_cvt_pk_bf16_f32 v92, v89, v90
	ds_write2_b32 v80, v91, v92 offset0:88 offset1:156
	s_waitcnt lgkmcnt(5)
	v_fma_f32 v92, v71, v89, v116
	v_fma_f32 v91, v75, v90, v108
	v_fma_f32 v89, v70, v89, v91
	v_fma_f32 v90, v70, v90, v92
	v_fma_f32 v92, v75, v90, v109
	v_cvt_pk_bf16_f32 v91, v89, v90
	v_fma_f32 v93, v71, v89, v117
	v_fma_f32 v89, v70, v89, v92
	v_fma_f32 v90, v70, v90, v93
	v_cvt_pk_bf16_f32 v92, v89, v90
	ds_write2_b32 v79, v91, v92 offset0:96 offset1:164
	v_fma_f32 v92, v71, v89, v118
	v_fma_f32 v91, v75, v90, v110
	v_fma_f32 v89, v70, v89, v91
	v_fma_f32 v90, v70, v90, v92
	v_fma_f32 v92, v75, v90, v111
	v_cvt_pk_bf16_f32 v91, v89, v90
	v_fma_f32 v93, v71, v89, v119
	v_fma_f32 v89, v70, v89, v92
	v_fma_f32 v90, v70, v90, v93
	v_cvt_pk_bf16_f32 v92, v89, v90
	ds_write2_b32 v78, v91, v92 offset0:104 offset1:172
	s_waitcnt lgkmcnt(6)
	v_fma_f32 v92, v71, v89, v120
	v_fma_f32 v91, v75, v90, v112
	v_fma_f32 v89, v70, v89, v91
	v_fma_f32 v90, v70, v90, v92
	v_fma_f32 v92, v75, v90, v113
	v_cvt_pk_bf16_f32 v91, v89, v90
	v_fma_f32 v93, v71, v89, v121
	v_fma_f32 v89, v70, v89, v92
	v_fma_f32 v90, v70, v90, v93
	v_cvt_pk_bf16_f32 v92, v89, v90
	ds_write2_b32 v77, v91, v92 offset0:112 offset1:180
	v_fma_f32 v92, v71, v89, v122
	v_fma_f32 v91, v75, v90, v114
	v_fma_f32 v89, v70, v89, v91
	v_fma_f32 v90, v70, v90, v92
	v_fma_f32 v92, v75, v90, v115
	v_cvt_pk_bf16_f32 v91, v89, v90
	v_fma_f32 v93, v71, v89, v123
	v_fma_f32 v89, v70, v89, v92
	v_fma_f32 v90, v70, v90, v93
	v_cvt_pk_bf16_f32 v92, v89, v90
	ds_write2_b32 v76, v91, v92 offset0:120 offset1:188
.LBB0_378:
	s_waitcnt lgkmcnt(0)
	s_barrier
	s_and_saveexec_b64 s[4:5], vcc
	v_add_u32_e32 v91, v84, v85
	s_waitcnt vmcnt(3)
	ds_write_b128 v91, v[56:59] offset:29184
	s_or_b64 exec, exec, s[4:5]
	s_add_i32 s4, s10, 5
	s_min_u32 s5, s4, 0x10a
	s_lshl_b32 s5, s5, 4
	s_cmp_lt_u32 s4, 11
	s_movk_i32 s4, 0xff50
	s_movk_i32 s11, 0xaf
	s_cselect_b32 s4, 0x50, s4
	s_cselect_b32 s11, s11, 0x10af
	s_cselect_b32 s12, s8, s2
	s_add_i32 s13, s5, s4
	s_sub_i32 s11, s11, s5
	s_and_b64 s[4:5], s[6:7], exec
	s_cselect_b32 s4, s13, s11
	s_add_i32 s4, s4, s12
	v_add_u32_e32 v56, s4, v74
	v_mad_u32_u24 v56, v56, s63, v82
	v_ashrrev_i32_e32 v57, 31, v56
	v_lshl_add_u64 v[56:57], v[56:57], 1, s[82:83]
	global_load_dwordx4 v[56:59], v[56:57], off nt
	ds_read_b128 v[92:95], v83 offset:5120
	ds_read_b128 v[96:99], v83 offset:5136
	ds_read_b128 v[100:103], v83
	ds_read_b128 v[104:107], v83 offset:16
	ds_read_b128 v[108:111], v83 offset:32
	ds_read_b128 v[112:115], v83 offset:48
	ds_read_b128 v[116:119], v83 offset:5152
	ds_read_b128 v[120:123], v83 offset:5168
	s_waitcnt lgkmcnt(7)
	v_fma_f32 v92, v71, v89, v92
	s_waitcnt lgkmcnt(5)
	v_fma_f32 v91, v75, v90, v100
	s_waitcnt lgkmcnt(0)
	v_fma_f32 v89, v70, v89, v91
	v_fma_f32 v90, v70, v90, v92
	v_fma_f32 v92, v75, v90, v101
	v_fma_f32 v93, v71, v89, v93
	v_cvt_pk_bf16_f32 v91, v89, v90
	v_fma_f32 v92, v70, v89, v92
	v_fma_f32 v90, v70, v90, v93
	v_add_u32_e32 v89, 0x5000, v87
	v_cvt_pk_bf16_f32 v93, v92, v90
	ds_write2_b32 v89, v91, v93 offset1:68
	v_fma_f32 v91, v75, v90, v102
	v_fma_f32 v93, v71, v92, v94
	v_fma_f32 v91, v70, v92, v91
	v_fma_f32 v90, v70, v90, v93
	v_fma_f32 v93, v75, v90, v103
	v_cvt_pk_bf16_f32 v92, v91, v90
	v_fma_f32 v94, v71, v91, v95
	v_fma_f32 v91, v70, v91, v93
	v_fma_f32 v90, v70, v90, v94
	v_cvt_pk_bf16_f32 v93, v91, v90
	ds_write2_b32 v89, v92, v93 offset0:136 offset1:204
	v_fma_f32 v93, v71, v91, v96
	s_waitcnt lgkmcnt(6)
	v_fma_f32 v92, v75, v90, v104
	v_fma_f32 v91, v70, v91, v92
	v_fma_f32 v90, v70, v90, v93
	v_fma_f32 v93, v75, v90, v105
	v_fma_f32 v94, v71, v91, v97
	v_cvt_pk_bf16_f32 v92, v91, v90
	v_fma_f32 v91, v70, v91, v93
	v_fma_f32 v93, v70, v90, v94
	v_add_u32_e32 v90, 0x5400, v87
	v_cvt_pk_bf16_f32 v94, v91, v93
	ds_write2_b32 v90, v92, v94 offset0:16 offset1:84
	v_fma_f32 v92, v75, v93, v106
	v_fma_f32 v94, v71, v91, v98
	v_fma_f32 v91, v70, v91, v92
	v_fma_f32 v92, v70, v93, v94
	v_fma_f32 v94, v75, v92, v107
	v_cvt_pk_bf16_f32 v93, v91, v92
	v_fma_f32 v95, v71, v91, v99
	v_fma_f32 v91, v70, v91, v94
	v_fma_f32 v92, v70, v92, v95
	v_cvt_pk_bf16_f32 v94, v91, v92
	ds_write2_b32 v90, v93, v94 offset0:152 offset1:220
	s_waitcnt lgkmcnt(5)
	v_fma_f32 v94, v71, v91, v116
	v_fma_f32 v93, v75, v92, v108
	v_fma_f32 v91, v70, v91, v93
	v_fma_f32 v92, v70, v92, v94
	v_fma_f32 v94, v75, v92, v109
	v_fma_f32 v95, v71, v91, v117
	v_cvt_pk_bf16_f32 v93, v91, v92
	v_fma_f32 v91, v70, v91, v94
	v_fma_f32 v94, v70, v92, v95
	v_add_u32_e32 v92, 0x5800, v87
	v_cvt_pk_bf16_f32 v95, v91, v94
	ds_write2_b32 v92, v93, v95 offset0:32 offset1:100
	v_fma_f32 v93, v75, v94, v110
	v_fma_f32 v95, v71, v91, v118
	v_fma_f32 v91, v70, v91, v93
	v_fma_f32 v93, v70, v94, v95
	v_fma_f32 v95, v75, v93, v111
	v_cvt_pk_bf16_f32 v94, v91, v93
	v_fma_f32 v96, v71, v91, v119
	v_fma_f32 v91, v70, v91, v95
	v_fma_f32 v93, v70, v93, v96
	v_cvt_pk_bf16_f32 v95, v91, v93
	ds_write2_b32 v92, v94, v95 offset0:168 offset1:236
	s_waitcnt lgkmcnt(6)
	v_fma_f32 v95, v71, v91, v120
	v_fma_f32 v94, v75, v93, v112
	v_fma_f32 v91, v70, v91, v94
	v_fma_f32 v93, v70, v93, v95
	v_fma_f32 v95, v75, v93, v113
	v_fma_f32 v96, v71, v91, v121
	v_cvt_pk_bf16_f32 v94, v91, v93
	v_fma_f32 v95, v70, v91, v95
	v_fma_f32 v93, v70, v93, v96
	v_add_u32_e32 v91, 0x5c00, v87
	v_cvt_pk_bf16_f32 v96, v95, v93
	ds_write2_b32 v91, v94, v96 offset0:48 offset1:116
	v_fma_f32 v94, v75, v93, v114
	v_fma_f32 v96, v71, v95, v122
	v_fma_f32 v94, v70, v95, v94
	v_fma_f32 v93, v70, v93, v96
	v_fma_f32 v96, v75, v93, v115
	v_cvt_pk_bf16_f32 v95, v94, v93
	v_fma_f32 v97, v71, v94, v123
	v_fma_f32 v94, v70, v94, v96
	v_fma_f32 v93, v70, v93, v97
	v_cvt_pk_bf16_f32 v96, v94, v93
	ds_write2_b32 v91, v95, v96 offset0:184 offset1:252
	s_waitcnt lgkmcnt(0)
	s_barrier
	s_and_saveexec_b64 s[4:5], vcc
	v_add_u32_e32 v95, v84, v85
	s_waitcnt vmcnt(3)
	ds_write_b128 v95, v[64:67] offset:29696
	s_or_b64 exec, exec, s[4:5]
	s_add_i32 s4, s10, 6
	s_min_u32 s5, s4, 0x10a
	s_lshl_b32 s5, s5, 4
	s_cmp_lt_u32 s4, 11
	s_movk_i32 s4, 0xff50
	s_movk_i32 s11, 0xaf
	s_cselect_b32 s4, 0x50, s4
	s_cselect_b32 s11, s11, 0x10af
	s_cselect_b32 s12, s8, s2
	s_add_i32 s13, s5, s4
	s_sub_i32 s11, s11, s5
	s_and_b64 s[4:5], s[6:7], exec
	s_cselect_b32 s4, s13, s11
	s_add_i32 s4, s4, s12
	v_add_u32_e32 v64, s4, v74
	v_mad_u32_u24 v64, v64, s63, v82
	v_ashrrev_i32_e32 v65, 31, v64
	v_lshl_add_u64 v[64:65], v[64:65], 1, s[82:83]
	global_load_dwordx4 v[64:67], v[64:65], off nt
	ds_read_b128 v[96:99], v83 offset:15360
	ds_read_b128 v[100:103], v83 offset:15376
	ds_read_b128 v[104:107], v83 offset:10240
	ds_read_b128 v[108:111], v83 offset:10256
	ds_read_b128 v[112:115], v83 offset:10272
	ds_read_b128 v[116:119], v83 offset:10288
	ds_read_b128 v[120:123], v83 offset:15392
	ds_read_b128 v[124:127], v83 offset:15408
	s_waitcnt lgkmcnt(7)
	v_fma_f32 v96, v71, v94, v96
	s_waitcnt lgkmcnt(5)
	v_fma_f32 v95, v75, v93, v104
	s_waitcnt lgkmcnt(0)
	s_add_i32 s10, s10, 7
	v_fma_f32 v94, v70, v94, v95
	v_fma_f32 v93, v70, v93, v96
	s_cmpk_gt_u32 s10, 0x10e
	v_fma_f32 v96, v75, v93, v105
	v_cvt_pk_bf16_f32 v95, v94, v93
	v_fma_f32 v97, v71, v94, v97
	v_fma_f32 v94, v70, v94, v96
	v_fma_f32 v93, v70, v93, v97
	v_cvt_pk_bf16_f32 v96, v94, v93
	ds_write2_b32 v88, v95, v96 offset0:64 offset1:132
	v_fma_f32 v96, v71, v94, v98
	v_fma_f32 v95, v75, v93, v106
	v_fma_f32 v94, v70, v94, v95
	v_fma_f32 v93, v70, v93, v96
	v_fma_f32 v96, v75, v93, v107
	v_cvt_pk_bf16_f32 v95, v94, v93
	v_fma_f32 v97, v71, v94, v99
	v_fma_f32 v94, v70, v94, v96
	v_fma_f32 v93, v70, v93, v97
	v_cvt_pk_bf16_f32 v96, v94, v93
	ds_write2_b32 v86, v95, v96 offset0:72 offset1:140
	v_fma_f32 v96, v71, v94, v100
	s_waitcnt lgkmcnt(6)
	v_fma_f32 v95, v75, v93, v108
	v_fma_f32 v94, v70, v94, v95
	v_fma_f32 v93, v70, v93, v96
	v_fma_f32 v96, v75, v93, v109
	v_cvt_pk_bf16_f32 v95, v94, v93
	v_fma_f32 v97, v71, v94, v101
	v_fma_f32 v94, v70, v94, v96
	v_fma_f32 v93, v70, v93, v97
	v_cvt_pk_bf16_f32 v96, v94, v93
	ds_write2_b32 v81, v95, v96 offset0:80 offset1:148
	v_fma_f32 v96, v71, v94, v102
	v_fma_f32 v95, v75, v93, v110
	v_fma_f32 v94, v70, v94, v95
	v_fma_f32 v93, v70, v93, v96
	v_fma_f32 v96, v75, v93, v111
	v_cvt_pk_bf16_f32 v95, v94, v93
	v_fma_f32 v97, v71, v94, v103
	v_fma_f32 v94, v70, v94, v96
	v_fma_f32 v93, v70, v93, v97
	v_cvt_pk_bf16_f32 v96, v94, v93
	ds_write2_b32 v80, v95, v96 offset0:88 offset1:156
	s_waitcnt lgkmcnt(5)
	v_fma_f32 v96, v71, v94, v120
	v_fma_f32 v95, v75, v93, v112
	v_fma_f32 v94, v70, v94, v95
	v_fma_f32 v93, v70, v93, v96
	v_fma_f32 v96, v75, v93, v113
	v_cvt_pk_bf16_f32 v95, v94, v93
	v_fma_f32 v97, v71, v94, v121
	v_fma_f32 v94, v70, v94, v96
	v_fma_f32 v93, v70, v93, v97
	v_cvt_pk_bf16_f32 v96, v94, v93
	ds_write2_b32 v79, v95, v96 offset0:96 offset1:164
	v_fma_f32 v96, v71, v94, v122
	v_fma_f32 v95, v75, v93, v114
	v_fma_f32 v94, v70, v94, v95
	v_fma_f32 v93, v70, v93, v96
	v_fma_f32 v96, v75, v93, v115
	v_cvt_pk_bf16_f32 v95, v94, v93
	v_fma_f32 v97, v71, v94, v123
	v_fma_f32 v94, v70, v94, v96
	v_fma_f32 v93, v70, v93, v97
	v_cvt_pk_bf16_f32 v96, v94, v93
	ds_write2_b32 v78, v95, v96 offset0:104 offset1:172
	s_waitcnt lgkmcnt(6)
	v_fma_f32 v96, v71, v94, v124
	v_fma_f32 v95, v75, v93, v116
	v_fma_f32 v94, v70, v94, v95
	v_fma_f32 v93, v70, v93, v96
	v_fma_f32 v96, v75, v93, v117
	v_cvt_pk_bf16_f32 v95, v94, v93
	v_fma_f32 v97, v71, v94, v125
	v_fma_f32 v94, v70, v94, v96
	v_fma_f32 v93, v70, v93, v97
	v_cvt_pk_bf16_f32 v96, v94, v93
	ds_write2_b32 v77, v95, v96 offset0:112 offset1:180
	v_fma_f32 v96, v71, v94, v126
	v_fma_f32 v95, v75, v93, v118
	v_fma_f32 v94, v70, v94, v95
	v_fma_f32 v93, v70, v93, v96
	v_fma_f32 v96, v75, v93, v119
	v_cvt_pk_bf16_f32 v95, v94, v93
	v_fma_f32 v97, v71, v94, v127
	v_fma_f32 v94, v70, v94, v96
	v_fma_f32 v93, v70, v93, v97
	v_cvt_pk_bf16_f32 v96, v94, v93
	ds_write2_b32 v76, v95, v96 offset0:120 offset1:188
	s_waitcnt lgkmcnt(0)
	s_barrier
	s_cbranch_scc1 .LBB0_373
	s_and_saveexec_b64 s[4:5], vcc
	s_cbranch_execz .LBB0_372
	v_add_u32_e32 v95, v84, v85
	s_waitcnt vmcnt(3)
	ds_write_b128 v95, v[60:63] offset:29184
	s_branch .LBB0_372

.LBB0_405:
	s_or_b64 exec, exec, s[6:7]
	v_readlane_b32 s0, v255, 33
	s_lshr_b32 s1, s0, 3
	s_bfe_i32 s0, s65, 0x10000
	s_bfe_u32 s11, s65, 0x20001
	s_and_b32 s2, s0, 0xc0
	s_lshl_b32 s38, s1, 8
	s_and_b32 s0, s0, 0xff
	s_waitcnt lgkmcnt(0)
	s_and_b32 s12, s65, 1
	s_lshl_b32 s37, s11, 6
	s_or_b32 s2, s2, s38
	s_or_b32 s24, s0, s38
	s_cmp_eq_u32 s12, 0
	s_cselect_b64 s[26:27], -1, 0
	v_mov_b32_e32 v4, v68
	s_and_b64 s[4:5], s[26:27], exec
	s_cselect_b32 s39, 1, -1
	s_lshl_b32 s25, s11, 7
	s_lshl_b32 s0, s12, 6
	v_ashrrev_i32_e32 v6, 3, v4
	v_lshlrev_b32_e32 v4, 3, v4
	s_or_b32 s13, s25, s0
	v_add_u32_e32 v5, s2, v6
	v_and_b32_e32 v7, 56, v4
	s_addk_i32 s13, 0x900
	v_mul_lo_u32 v6, v6, s39
	v_or_b32_e32 v4, s13, v7
	v_add_u32_e32 v6, s24, v6
	v_mad_u32_u24 v4, v5, s63, v4
	v_mul_u32_u24_e32 v6, 0x300, v6
	v_ashrrev_i32_e32 v5, 31, v4
	v_or3_b32 v6, v6, s37, v7
	v_lshl_add_u64 v[4:5], v[4:5], 1, s[82:83]
	v_ashrrev_i32_e32 v7, 31, v6
	v_lshl_add_u64 v[6:7], v[6:7], 1, s[84:85]
	global_load_dwordx4 v[32:35], v[4:5], off nt
	global_load_dwordx4 v[28:31], v[6:7], off nt
	global_load_dwordx4 v[20:23], v[6:7], off offset:512 nt
	global_load_dwordx4 v[24:27], v[6:7], off offset:1024 nt
	v_cmp_lt_i32_e32 vcc, 63, v68
	v_cmp_gt_i32_e64 s[6:7], 64, v68
	s_waitcnt vmcnt(7)
	v_mov_b32_e32 v55, 0
	v_mul_lo_u32 v54, s39, v68
	s_waitcnt vmcnt(6)
	v_mov_b32_e32 v56, 0
	v_mov_b32_e32 v57, 0
	s_and_saveexec_b64 s[8:9], s[6:7]
	s_cbranch_execz .LBB0_407
	v_add_u32_e32 v4, s2, v68
	s_lshl_b32 s2, s12, 2
	s_or_b32 s2, s11, s2
	v_lshl_or_b32 v180, v4, 4, s2
	v_lshl_add_u64 v[4:5], v[180:181], 2, s[86:87]
	global_load_dword v56, v[4:5], off nt
	v_mul_lo_u32 v4, s39, v68
	v_add_lshl_u32 v4, s24, v4, 4
	v_or3_b32 v180, v4, s2, 8
	v_lshl_add_u64 v[4:5], v[180:181], 2, s[86:87]
	global_load_dword v57, v[4:5], off nt
.LBB0_407:
	s_or_b64 exec, exec, s[8:9]
	s_add_i32 s4, s0, s38
	s_add_i32 s4, s4, 64
	v_mov_b32_e32 v4, v68
	s_and_b64 s[8:9], s[26:27], exec
	s_cselect_b32 s2, 64, 0xbf
	v_ashrrev_i32_e32 v6, 3, v4
	s_or_b32 s2, s2, s38
	v_add_u32_e32 v5, s4, v6
	v_lshlrev_b32_e32 v4, 3, v4
	v_mul_lo_u32 v6, v6, s39
	v_and_b32_e32 v7, 56, v4
	v_add_u32_e32 v6, s2, v6
	v_or_b32_e32 v4, s13, v7
	v_mul_u32_u24_e32 v6, 0x300, v6
	v_mad_u32_u24 v4, v5, s63, v4
	v_or3_b32 v6, v6, s37, v7
	v_ashrrev_i32_e32 v5, 31, v4
	v_ashrrev_i32_e32 v7, 31, v6
	v_lshl_add_u64 v[4:5], v[4:5], 1, s[82:83]
	v_lshl_add_u64 v[8:9], v[6:7], 1, s[84:85]
	global_load_dwordx4 v[16:19], v[4:5], off nt
	global_load_dwordx4 v[12:15], v[8:9], off nt
	s_nop 0
	global_load_dwordx4 v[4:7], v[8:9], off offset:512 nt
	s_nop 0
	global_load_dwordx4 v[8:11], v[8:9], off offset:1024 nt
	v_mov_b32_e32 v58, 0
	s_and_saveexec_b64 s[8:9], s[6:7]
	s_cbranch_execz .LBB0_409
	v_add_u32_e32 v36, s4, v68
	s_lshl_b32 s4, s12, 2
	s_or_b32 s4, s11, s4
	v_lshl_or_b32 v180, v36, 4, s4
	v_lshl_add_u64 v[36:37], v[180:181], 2, s[86:87]
	global_load_dword v55, v[36:37], off nt
	v_mul_lo_u32 v36, s39, v68
	v_add_lshl_u32 v36, s2, v36, 4
	v_or3_b32 v180, v36, s4, 8
	v_lshl_add_u64 v[36:37], v[180:181], 2, s[86:87]
	global_load_dword v58, v[36:37], off nt

.LBB0_411:
	s_or_b64 exec, exec, s[4:5]
	v_mov_b32_e32 v36, v68
	s_waitcnt lgkmcnt(0)
	s_barrier
	s_waitcnt vmcnt(5)
	v_lshlrev_b32_e32 v42, 16, v20
	v_ashrrev_i32_e32 v37, 3, v36
	v_lshlrev_b32_e32 v36, 4, v36
	v_mul_lo_u32 v50, v37, s61
	v_and_b32_e32 v51, 0x70, v36
	v_add3_u32 v52, 0, v50, v51
	ds_write_b128 v52, v[32:35]
	v_lshl_add_u32 v32, v37, 2, 0
	v_add_u32_e32 v32, 0x1f800, v32
	ds_read_b32 v53, v32
	v_and_b32_e32 v43, 0xffff0000, v20
	v_and_b32_e32 v33, 0xffff0000, v28
	v_lshlrev_b32_e32 v44, 16, v21
	v_and_b32_e32 v45, 0xffff0000, v21
	s_waitcnt lgkmcnt(0)
	v_mul_f32_e32 v32, 0x3fb8aa3b, v53
	v_exp_f32_e32 v40, v32
	v_lshlrev_b32_e32 v32, 16, v28
	v_lshlrev_b32_e32 v48, 16, v31
	v_and_b32_e32 v49, 0xffff0000, v31
	v_pk_mul_f32 v[34:35], v[40:41], v[42:43] op_sel_hi:[0,1]
	v_cvt_pk_bf16_f32 v36, v34, v35
	v_lshlrev_b32_e32 v34, 16, v29
	v_and_b32_e32 v35, 0xffff0000, v29
	v_pk_mul_f32 v[32:33], v[40:41], v[32:33] op_sel_hi:[0,1]
	v_pk_mul_f32 v[34:35], v[40:41], v[34:35] op_sel_hi:[0,1]
	v_cvt_pk_bf16_f32 v32, v32, v33
	v_cvt_pk_bf16_f32 v33, v34, v35
	v_pk_mul_f32 v[34:35], v[40:41], v[44:45] op_sel_hi:[0,1]
	v_cvt_pk_bf16_f32 v37, v34, v35
	v_lshlrev_b32_e32 v34, 16, v30
	v_and_b32_e32 v35, 0xffff0000, v30
	v_pk_mul_f32 v[34:35], v[40:41], v[34:35] op_sel_hi:[0,1]
	v_pk_mul_f32 v[48:49], v[40:41], v[48:49] op_sel_hi:[0,1]
	v_cvt_pk_bf16_f32 v34, v34, v35
	v_lshlrev_b32_e32 v46, 16, v22
	v_and_b32_e32 v47, 0xffff0000, v22
	v_cvt_pk_bf16_f32 v35, v48, v49
	v_lshlrev_b32_e32 v48, 16, v23
	v_and_b32_e32 v49, 0xffff0000, v23
	v_pk_mul_f32 v[38:39], v[40:41], v[46:47] op_sel_hi:[0,1]
	v_pk_mul_f32 v[40:41], v[40:41], v[48:49] op_sel_hi:[0,1]
	s_add_i32 s40, 0, 0x16800
	v_cvt_pk_bf16_f32 v38, v38, v39
	v_cvt_pk_bf16_f32 v39, v40, v41
	ds_write_b128 v52, v[32:35] offset:27648
	ds_write_b128 v52, v[36:39] offset:18432
	v_add3_u32 v32, s40, v50, v51
	s_add_i32 s41, 0, 0x18c00
	ds_write_b128 v32, v[28:31]
	v_add3_u32 v28, s41, v50, v51
	v_readlane_b32 s4, v255, 2
	ds_write_b128 v28, v[20:23]
	s_waitcnt vmcnt(4)
	ds_write_b128 v52, v[24:27] offset:46080
	v_mov_b32_e32 v20, s4
	ds_read_b32 v20, v20
	s_sub_i32 s15, s38, s0
	s_addk_i32 s15, 0x80
	s_sub_i32 s14, s38, s12
	s_addk_i32 s14, 0x80
	s_waitcnt lgkmcnt(0)
	v_sub_f32_e32 v20, v20, v53
	v_mul_f32_e32 v20, 0x3fb8aa3b, v20
	v_exp_f32_e32 v24, v20
	s_nop 0
	v_pk_mul_f32 v[20:21], v[24:25], v[42:43] op_sel_hi:[0,1]
	v_pk_mul_f32 v[22:23], v[24:25], v[44:45] op_sel_hi:[0,1]
	v_cvt_pk_bf16_f32 v20, v20, v21
	v_cvt_pk_bf16_f32 v21, v22, v23
	v_pk_mul_f32 v[22:23], v[24:25], v[46:47] op_sel_hi:[0,1]
	v_pk_mul_f32 v[24:25], v[24:25], v[48:49] op_sel_hi:[0,1]
	v_cvt_pk_bf16_f32 v22, v22, v23
	v_cvt_pk_bf16_f32 v23, v24, v25
	ds_write_b128 v52, v[20:23] offset:36864
	v_mov_b32_e32 v20, v68
	s_waitcnt lgkmcnt(0)
	s_barrier
	s_nop 0
	v_ashrrev_i32_e32 v22, 3, v20
	v_add_u32_e32 v21, s15, v22
	v_lshlrev_b32_e32 v20, 3, v20
	v_mul_lo_u32 v22, v22, s39
	v_and_b32_e32 v23, 56, v20
	v_add_u32_e32 v22, s14, v22
	v_or_b32_e32 v20, s13, v23
	v_mul_u32_u24_e32 v22, 0x300, v22
	v_mad_u32_u24 v20, v21, s63, v20
	v_or3_b32 v22, v22, s37, v23
	v_ashrrev_i32_e32 v21, 31, v20
	v_ashrrev_i32_e32 v23, 31, v22
	v_lshl_add_u64 v[20:21], v[20:21], 1, s[82:83]
	v_lshl_add_u64 v[24:25], v[22:23], 1, s[84:85]
	global_load_dwordx4 v[32:35], v[20:21], off nt
	global_load_dwordx4 v[28:31], v[24:25], off nt
	s_nop 0
	global_load_dwordx4 v[20:23], v[24:25], off offset:512 nt
	s_nop 0
	global_load_dwordx4 v[24:27], v[24:25], off offset:1024 nt
	s_and_saveexec_b64 s[4:5], vcc
	s_xor_b64 s[4:5], exec, s[4:5]
	s_cbranch_execz .LBB0_539
	s_lshl_b32 s8, s12, 2
	s_or_b32 s13, s11, s8
	v_mul_lo_u32 v54, s39, v68
	s_or_saveexec_b64 s[8:9], s[4:5]
	v_mov_b32_e32 v59, s13
	s_xor_b64 exec, exec, s[8:9]
	s_cbranch_execnz .LBB0_540

.LBB0_417:
	v_mul_u32_u24_e32 v98, 0x90, v36
	v_add_u32_e32 v41, s4, v98
	v_lshrrev_b32_e32 v36, 1, v68
	v_readlane_b32 s4, v255, 2
	v_and_or_b32 v99, v36, 24, v37
	s_add_i32 s43, s34, 0
	v_mov_b32_e32 v36, s4
	s_waitcnt lgkmcnt(0)
	s_barrier
	ds_read_b32 v42, v36
	ds_read_b128 v[88:91], v77 offset:9216
	v_mov_b32_e32 v36, s43
	v_mad_u32_u24 v43, v99, s61, v36
	ds_read_b128 v[36:39], v62 offset:64512
	v_add_u32_e32 v84, v43, v50
	ds_read_b64_tr_b16 v[92:93], v84 offset:36864
	ds_read_b64_tr_b16 v[94:95], v84 offset:37440
	ds_read_b128 v[100:103], v78 offset:9216
	v_add_u32_e32 v83, v41, v47
	s_waitcnt lgkmcnt(5)
	v_mul_f32_e32 v41, 0x3fb8aa3b, v42
	v_exp_f32_e32 v41, v41
	s_waitcnt lgkmcnt(3)
	v_mfma_f32_16x16x32_bf16 v[88:91], v[36:39], v[88:91], 0
	ds_read_b128 v[104:107], v62 offset:64576
	ds_read_b128 v[108:111], v77 offset:64512
	v_mul_f32_e32 v112, 0, v41
	v_mov_b32_e32 v113, v112
	s_waitcnt lgkmcnt(2)
	v_mfma_f32_16x16x32_bf16 v[36:39], v[36:39], v[100:103], 0
	ds_read_b128 v[100:103], v78 offset:64512
	v_mov_b32_e32 v114, v112
	v_mov_b32_e32 v115, v112
	ds_read_b128 v[116:119], v83
	ds_read_b64_tr_b16 v[120:121], v84 offset:41472
	ds_read_b128 v[124:127], v77 offset:9280
	s_waitcnt lgkmcnt(4)
	v_mfma_f32_16x16x32_bf16 v[108:111], v[92:95], v[108:111], v[112:115]
	v_mul_lo_u32 v85, v40, s39
	s_add_i32 s44, 0, 0x14400
	s_and_b64 s[4:5], s[26:27], exec
	s_waitcnt lgkmcnt(3)
	v_mfma_f32_16x16x32_bf16 v[100:103], v[92:95], v[100:103], v[112:115]
	ds_read_b64_tr_b16 v[122:123], v84 offset:42048
	ds_read_b128 v[92:95], v78 offset:9280
	s_nop 0
	ds_read_b128 v[112:115], v77 offset:64576
	ds_read_b128 v[128:131], v78 offset:64576
	ds_read_b128 v[132:135], v83 offset:64
	s_cselect_b32 s4, 0xc0, 63
	s_waitcnt lgkmcnt(5)
	v_mfma_f32_16x16x32_bf16 v[124:127], v[104:107], v[124:127], v[88:91]
	s_or_b32 s45, s4, s38
	s_add_i32 s35, s25, 0x900
	s_and_b64 s[4:5], s[26:27], exec
	s_waitcnt lgkmcnt(3)
	v_mfma_f32_16x16x32_bf16 v[104:107], v[104:107], v[92:95], v[36:39]
	v_add_u32_e32 v91, s44, v49
	v_add_u32_e32 v87, s34, v91
	v_add_u32_e32 v93, s44, v48
	s_waitcnt lgkmcnt(2)
	v_mfma_f32_16x16x32_bf16 v[36:39], v[120:123], v[112:115], v[108:111]
	v_add_u32_e32 v87, v87, v46
	v_add_u32_e32 v90, s34, v93
	s_cselect_b32 s4, s92, 0x1b485000
	ds_read_b128 v[108:111], v77 offset:27648
	s_waitcnt lgkmcnt(2)
	v_mfma_f32_16x16x32_bf16 v[40:43], v[120:123], v[128:131], v[100:103]
	s_nop 2
	ds_read_b128 v[100:103], v77 offset:27712
	ds_read_b128 v[112:115], v78 offset:27648
	ds_read_b128 v[120:123], v78 offset:27712
	v_cvt_pk_bf16_f32 v88, v36, v37
	s_waitcnt lgkmcnt(3)
	v_mfma_f32_16x16x32_bf16 v[108:111], v[116:119], v[108:111], v[124:127]
	v_cvt_pk_bf16_f32 v89, v38, v39
	ds_write_b64 v87, v[88:89]
	v_add_u32_e32 v89, s24, v85
	s_waitcnt lgkmcnt(3)
	v_mfma_f32_16x16x32_bf16 v[100:103], v[132:135], v[100:103], v[108:111]
	v_cvt_pk_bf16_f32 v94, v40, v41
	v_cvt_pk_bf16_f32 v95, v42, v43
	v_add_u32_e32 v88, v90, v46
	s_waitcnt lgkmcnt(2)
	v_mfma_f32_16x16x32_bf16 v[104:107], v[116:119], v[112:115], v[104:107]
	v_lshl_or_b32 v89, v89, 10, s33
	v_mul_lo_u32 v86, v86, s39
	s_add_u32 s28, s78, s4
	ds_write_b64 v88, v[94:95]
	v_cvt_pk_bf16_f32 v94, v100, v101
	v_add_u32_e32 v100, s37, v89
	v_mov_b32_e32 v101, v181
	s_addc_u32 s29, s79, 0
	s_waitcnt lgkmcnt(2)
	v_mfma_f32_16x16x32_bf16 v[104:107], v[132:135], v[120:123], v[104:107]
	v_lshl_add_u64 v[100:101], v[100:101], 0, v[180:181]
	v_add_u32_e32 v89, s24, v86
	v_cvt_pk_bf16_f32 v95, v102, v103
	v_lshl_add_u64 v[100:101], v[100:101], 1, s[28:29]
	v_lshl_or_b32 v89, v89, 10, s33
	global_store_dwordx2 v[100:101], v[94:95], off offset:1024
	v_add_u32_e32 v100, s37, v89
	v_mov_b32_e32 v101, v181
	v_lshl_add_u64 v[100:101], v[100:101], 0, v[180:181]
	v_cvt_pk_bf16_f32 v94, v104, v105
	v_cvt_pk_bf16_f32 v95, v106, v107
	v_lshl_add_u64 v[100:101], v[100:101], 1, s[28:29]
	v_mov_b32_e32 v89, v68
	global_store_dwordx2 v[100:101], v[94:95], off offset:1024
	s_waitcnt vmcnt(7)
	v_lshlrev_b32_e32 v94, 16, v4
	v_ashrrev_i32_e32 v90, 3, v89
	v_lshlrev_b32_e32 v89, 4, v89
	v_mul_lo_u32 v92, v90, s61
	v_and_b32_e32 v89, 0x70, v89
	v_add3_u32 v97, 0, v92, v89
	ds_write_b128 v97, v[16:19]
	v_lshl_add_u32 v16, v90, 2, 0
	v_add_u32_e32 v16, 0x1fa00, v16
	ds_read_b32 v112, v16
	v_and_b32_e32 v95, 0xffff0000, v4
	v_and_b32_e32 v17, 0xffff0000, v12
	v_lshlrev_b32_e32 v104, 16, v5
	v_and_b32_e32 v105, 0xffff0000, v5
	s_waitcnt lgkmcnt(0)
	v_mul_f32_e32 v16, 0x3fb8aa3b, v112
	v_exp_f32_e32 v90, v16
	v_lshlrev_b32_e32 v16, 16, v12
	v_lshlrev_b32_e32 v108, 16, v15
	v_and_b32_e32 v109, 0xffff0000, v15
	v_pk_mul_f32 v[18:19], v[90:91], v[94:95] op_sel_hi:[0,1]
	v_cvt_pk_bf16_f32 v100, v18, v19
	v_lshlrev_b32_e32 v18, 16, v13
	v_and_b32_e32 v19, 0xffff0000, v13
	v_pk_mul_f32 v[16:17], v[90:91], v[16:17] op_sel_hi:[0,1]
	v_pk_mul_f32 v[18:19], v[90:91], v[18:19] op_sel_hi:[0,1]
	v_cvt_pk_bf16_f32 v16, v16, v17
	v_cvt_pk_bf16_f32 v17, v18, v19
	v_pk_mul_f32 v[18:19], v[90:91], v[104:105] op_sel_hi:[0,1]
	v_cvt_pk_bf16_f32 v101, v18, v19
	v_lshlrev_b32_e32 v18, 16, v14
	v_and_b32_e32 v19, 0xffff0000, v14
	v_pk_mul_f32 v[18:19], v[90:91], v[18:19] op_sel_hi:[0,1]
	v_pk_mul_f32 v[108:109], v[90:91], v[108:109] op_sel_hi:[0,1]
	v_cvt_pk_bf16_f32 v18, v18, v19
	v_lshlrev_b32_e32 v106, 16, v6
	v_and_b32_e32 v107, 0xffff0000, v6
	v_cvt_pk_bf16_f32 v19, v108, v109
	v_lshlrev_b32_e32 v108, 16, v7
	v_and_b32_e32 v109, 0xffff0000, v7
	v_readlane_b32 s4, v255, 4
	v_pk_mul_f32 v[102:103], v[90:91], v[106:107] op_sel_hi:[0,1]
	v_pk_mul_f32 v[110:111], v[90:91], v[108:109] op_sel_hi:[0,1]
	v_add3_u32 v90, s4, v92, v89
	v_cvt_pk_bf16_f32 v102, v102, v103
	v_cvt_pk_bf16_f32 v103, v110, v111
	ds_write_b128 v90, v[16:19]
	ds_write_b128 v97, v[100:103] offset:18432
	v_add3_u32 v16, s40, v92, v89
	ds_write_b128 v16, v[12:15]
	v_add3_u32 v12, s41, v92, v89
	ds_write_b128 v12, v[4:7]
	s_waitcnt vmcnt(6)
	ds_write_b128 v97, v[8:11] offset:46080
	v_mov_b32_e32 v4, s72
	ds_read_b32 v4, v4
	v_readlane_b32 s4, v255, 6
	s_waitcnt lgkmcnt(0)
	v_sub_f32_e32 v4, v4, v112
	v_mul_f32_e32 v4, 0x3fb8aa3b, v4
	v_exp_f32_e32 v8, v4
	s_nop 0
	v_pk_mul_f32 v[4:5], v[8:9], v[94:95] op_sel_hi:[0,1]
	v_pk_mul_f32 v[6:7], v[8:9], v[104:105] op_sel_hi:[0,1]
	v_cvt_pk_bf16_f32 v4, v4, v5
	v_cvt_pk_bf16_f32 v5, v6, v7
	v_pk_mul_f32 v[6:7], v[8:9], v[106:107] op_sel_hi:[0,1]
	v_pk_mul_f32 v[8:9], v[8:9], v[108:109] op_sel_hi:[0,1]
	v_cvt_pk_bf16_f32 v6, v6, v7
	v_cvt_pk_bf16_f32 v7, v8, v9
	v_add3_u32 v8, s4, v92, v89
	ds_write_b128 v8, v[4:7]
	v_mov_b32_e32 v4, v68
	s_and_b64 s[4:5], s[26:27], exec
	s_waitcnt lgkmcnt(0)
	s_barrier
	s_cselect_b32 s4, 0xc0, 0
	v_ashrrev_i32_e32 v6, 3, v4
	s_or_b32 s24, s4, s38
	v_lshlrev_b32_e32 v4, 3, v4
	v_add_u32_e32 v5, s24, v6
	v_and_b32_e32 v7, 56, v4
	v_mul_lo_u32 v6, v6, s39
	v_or_b32_e32 v4, s35, v7
	v_add_u32_e32 v6, s45, v6
	v_or_b32_e32 v4, s0, v4
	v_mul_u32_u24_e32 v6, 0x300, v6
	v_mad_u32_u24 v4, v5, s63, v4
	v_or3_b32 v6, v6, s37, v7
	v_ashrrev_i32_e32 v5, 31, v4
	v_ashrrev_i32_e32 v7, 31, v6
	v_lshl_add_u64 v[4:5], v[4:5], 1, s[82:83]
	v_lshl_add_u64 v[16:17], v[6:7], 1, s[84:85]
	global_load_dwordx4 v[4:7], v[4:5], off nt
	s_nop 0
	global_load_dwordx4 v[8:11], v[16:17], off nt
	global_load_dwordx4 v[12:15], v[16:17], off offset:512 nt
	s_nop 0
	global_load_dwordx4 v[16:19], v[16:17], off offset:1024 nt
	v_or_b32_e32 v89, 8, v59
	s_and_saveexec_b64 s[4:5], s[6:7]
	s_cbranch_execz .LBB0_419
	v_add_u32_e32 v55, s24, v68
	v_lshl_add_u32 v94, v55, 4, v59
	v_mov_b32_e32 v95, v181
	v_lshl_add_u64 v[94:95], v[94:95], 2, s[86:87]
	v_add_u32_e32 v58, s45, v54
	global_load_dword v55, v[94:95], off nt
	v_lshl_add_u32 v94, v58, 4, v89
	v_mov_b32_e32 v95, v181
	v_lshl_add_u64 v[94:95], v[94:95], 2, s[86:87]
	global_load_dword v58, v[94:95], off nt

.LBB0_423:
	v_mov_b32_e32 v53, s72
	s_waitcnt lgkmcnt(0)
	s_barrier
	ds_read_b32 v53, v53
	v_mul_u32_u24_e32 v52, 0x90, v99
	v_add_u32_e32 v51, s44, v98
	s_add_i32 s43, s43, 0x1d400
	v_add_u32_e32 v99, s43, v52
	v_add_u32_e32 v98, v51, v47
	v_add_u32_e32 v100, s43, v50
	ds_read_b128 v[104:107], v98
	s_waitcnt lgkmcnt(1)
	v_mul_f32_e32 v51, 0x3fb8aa3b, v53
	v_add_u32_e32 v99, v99, v50
	v_exp_f32_e32 v102, v51
	ds_read_b128 v[108:111], v62 offset:64512
	ds_read_b128 v[112:115], v62 offset:64576
	ds_read_b64_tr_b16 v[50:51], v99
	v_add_u32_e32 v100, v100, v52
	ds_read_b128 v[116:119], v77 offset:9216
	ds_read_b64_tr_b16 v[52:53], v99 offset:576
	ds_read_b64_tr_b16 v[120:121], v100 offset:4608
	ds_read_b64_tr_b16 v[122:123], v100 offset:5184
	ds_read_b128 v[124:127], v77 offset:9280
	ds_read_b128 v[128:131], v78 offset:9216
	s_waitcnt lgkmcnt(5)
	v_mfma_f32_16x16x32_bf16 v[116:119], v[108:111], v[116:119], 0
	ds_read_b128 v[132:135], v78 offset:9280
	ds_read_b128 v[136:139], v77 offset:64512
	ds_read_b128 v[140:143], v77 offset:64576
	v_readlane_b32 s4, v255, 4
	v_pk_mul_f32 v[38:39], v[38:39], v[102:103] op_sel_hi:[1,0]
	s_waitcnt lgkmcnt(3)
	v_mfma_f32_16x16x32_bf16 v[108:111], v[108:111], v[128:131], 0
	ds_read_b128 v[128:131], v78 offset:64512
	v_add_u32_e32 v49, s4, v49
	v_pk_mul_f32 v[36:37], v[36:37], v[102:103] op_sel_hi:[1,0]
	v_pk_mul_f32 v[42:43], v[42:43], v[102:103] op_sel_hi:[1,0]
	v_pk_mul_f32 v[40:41], v[40:41], v[102:103] op_sel_hi:[1,0]
	v_add_u32_e32 v101, v49, v47
	s_waitcnt lgkmcnt(2)
	v_mfma_f32_16x16x32_bf16 v[36:39], v[50:53], v[136:139], v[36:39]
	ds_read_b128 v[136:139], v78 offset:64576
	v_add_u32_e32 v48, s4, v48
	v_add_u32_e32 v102, v48, v47
	s_waitcnt lgkmcnt(1)
	v_mfma_f32_16x16x32_bf16 v[40:43], v[50:53], v[128:131], v[40:43]
	v_add_u32_e32 v47, s34, v44
	v_add_u32_e32 v103, v47, v46
	v_mov_b32_e32 v47, v181
	v_mfma_f32_16x16x32_bf16 v[50:53], v[112:115], v[124:127], v[116:119]
	v_mfma_f32_16x16x32_bf16 v[108:111], v[112:115], v[132:135], v[108:111]
	ds_read_b128 v[112:115], v101
	s_nop 0
	ds_read_b128 v[116:119], v101 offset:64
	v_mfma_f32_16x16x32_bf16 v[36:39], v[120:123], v[140:143], v[36:39]
	s_waitcnt lgkmcnt(2)
	v_mfma_f32_16x16x32_bf16 v[40:43], v[120:123], v[136:139], v[40:43]
	s_waitcnt lgkmcnt(1)
	v_mfma_f32_16x16x32_bf16 v[48:51], v[104:107], v[112:115], v[50:53]
	ds_read_b128 v[112:115], v102
	ds_read_b128 v[120:123], v102 offset:64
	s_nop 1
	v_cvt_pk_bf16_f32 v44, v36, v37
	v_add_u32_e32 v52, s34, v45
	s_waitcnt lgkmcnt(1)
	v_mfma_f32_16x16x32_bf16 v[104:107], v[104:107], v[112:115], v[108:111]
	v_cvt_pk_bf16_f32 v45, v38, v39
	s_waitcnt vmcnt(7)
	v_and_b32_e32 v53, 0xffff0000, v21
	ds_read_b128 v[108:111], v98 offset:64
	s_waitcnt lgkmcnt(0)
	v_mfma_f32_16x16x32_bf16 v[48:51], v[108:111], v[116:119], v[48:51]
	ds_write_b64 v103, v[44:45]
	v_cvt_pk_bf16_f32 v44, v40, v41
	v_cvt_pk_bf16_f32 v45, v42, v43
	v_mfma_f32_16x16x32_bf16 v[106:109], v[108:111], v[120:123], v[104:107]
	s_nop 2
	v_add_u32_e32 v104, v52, v46
	ds_write_b64 v104, v[44:45]
	v_add_u32_e32 v44, s2, v85
	v_lshl_or_b32 v46, v44, 10, s33
	v_add_u32_e32 v46, s37, v46
	v_lshl_add_u64 v[46:47], v[46:47], 0, v[180:181]
	v_cvt_pk_bf16_f32 v44, v48, v49
	v_cvt_pk_bf16_f32 v45, v50, v51
	v_lshl_add_u64 v[46:47], v[46:47], 1, s[28:29]
	global_store_dwordx2 v[46:47], v[44:45], off offset:1024
	v_add_u32_e32 v44, s2, v86
	v_lshl_or_b32 v46, v44, 10, s33
	v_add_u32_e32 v46, s37, v46
	v_mov_b32_e32 v47, v181
	v_lshl_add_u64 v[46:47], v[46:47], 0, v[180:181]
	v_cvt_pk_bf16_f32 v44, v106, v107
	v_cvt_pk_bf16_f32 v45, v108, v109
	v_lshl_add_u64 v[46:47], v[46:47], 1, s[28:29]
	global_store_dwordx2 v[46:47], v[44:45], off offset:1024
	v_mov_b32_e32 v44, v68
	v_lshlrev_b32_e32 v50, 16, v20
	v_ashrrev_i32_e32 v45, 3, v44
	v_lshlrev_b32_e32 v44, 4, v44
	v_mul_lo_u32 v105, v45, s61
	v_and_b32_e32 v110, 0x70, v44
	v_add3_u32 v111, 0, v105, v110
	ds_write_b128 v111, v[32:35]
	v_lshl_add_u32 v32, v45, 2, 0
	v_add_u32_e32 v32, 0x1f800, v32
	ds_read_b32 v112, v32
	v_and_b32_e32 v51, 0xffff0000, v20
	v_and_b32_e32 v33, 0xffff0000, v28
	v_lshlrev_b32_e32 v52, 16, v21
	v_lshlrev_b32_e32 v108, 16, v31
	s_waitcnt lgkmcnt(0)
	v_mul_f32_e32 v32, 0x3fb8aa3b, v112
	v_exp_f32_e32 v48, v32
	v_lshlrev_b32_e32 v32, 16, v28
	v_and_b32_e32 v109, 0xffff0000, v31
	v_lshlrev_b32_e32 v106, 16, v22
	v_pk_mul_f32 v[34:35], v[48:49], v[50:51] op_sel_hi:[0,1]
	v_cvt_pk_bf16_f32 v44, v34, v35
	v_lshlrev_b32_e32 v34, 16, v29
	v_and_b32_e32 v35, 0xffff0000, v29
	v_pk_mul_f32 v[32:33], v[48:49], v[32:33] op_sel_hi:[0,1]
	v_pk_mul_f32 v[34:35], v[48:49], v[34:35] op_sel_hi:[0,1]
	v_cvt_pk_bf16_f32 v32, v32, v33
	v_cvt_pk_bf16_f32 v33, v34, v35
	v_pk_mul_f32 v[34:35], v[48:49], v[52:53] op_sel_hi:[0,1]
	v_cvt_pk_bf16_f32 v45, v34, v35
	v_lshlrev_b32_e32 v34, 16, v30
	v_and_b32_e32 v35, 0xffff0000, v30
	v_pk_mul_f32 v[34:35], v[48:49], v[34:35] op_sel_hi:[0,1]
	v_pk_mul_f32 v[108:109], v[48:49], v[108:109] op_sel_hi:[0,1]
	v_cvt_pk_bf16_f32 v34, v34, v35
	v_and_b32_e32 v107, 0xffff0000, v22
	v_cvt_pk_bf16_f32 v35, v108, v109
	v_lshlrev_b32_e32 v108, 16, v23
	v_and_b32_e32 v109, 0xffff0000, v23
	v_pk_mul_f32 v[46:47], v[48:49], v[106:107] op_sel_hi:[0,1]
	v_pk_mul_f32 v[48:49], v[48:49], v[108:109] op_sel_hi:[0,1]
	v_cvt_pk_bf16_f32 v46, v46, v47
	v_cvt_pk_bf16_f32 v47, v48, v49
	ds_write_b128 v111, v[32:35] offset:27648
	ds_write_b128 v111, v[44:47] offset:18432
	v_add3_u32 v32, s40, v105, v110
	ds_write_b128 v32, v[28:31]
	v_add3_u32 v28, s41, v105, v110
	v_readlane_b32 s2, v255, 2
	ds_write_b128 v28, v[20:23]
	s_waitcnt vmcnt(8)
	ds_write_b128 v111, v[24:27] offset:46080
	v_mov_b32_e32 v20, s2
	ds_read_b32 v20, v20
	s_lshl_b32 s2, s1, 12
	s_or_b32 s1, s2, 0x800
	s_or_b32 s2, s2, 0x700
	s_and_b64 s[4:5], s[26:27], exec
	s_waitcnt lgkmcnt(0)
	v_sub_f32_e32 v20, v20, v112
	v_mul_f32_e32 v20, 0x3fb8aa3b, v20
	v_exp_f32_e32 v24, v20
	s_movk_i32 s4, 0x10c0
	s_cselect_b32 s4, 0x100, s4
	s_add_i32 s31, s2, s4
	v_pk_mul_f32 v[20:21], v[24:25], v[50:51] op_sel_hi:[0,1]
	v_pk_mul_f32 v[22:23], v[24:25], v[52:53] op_sel_hi:[0,1]
	v_cvt_pk_bf16_f32 v20, v20, v21
	v_cvt_pk_bf16_f32 v21, v22, v23
	v_pk_mul_f32 v[22:23], v[24:25], v[106:107] op_sel_hi:[0,1]
	v_pk_mul_f32 v[24:25], v[24:25], v[108:109] op_sel_hi:[0,1]
	v_cvt_pk_bf16_f32 v22, v22, v23
	v_cvt_pk_bf16_f32 v23, v24, v25
	ds_write_b128 v111, v[20:23] offset:36864
	v_mov_b32_e32 v20, v68
	s_waitcnt lgkmcnt(0)
	s_barrier
	s_and_b64 s[4:5], s[26:27], exec
	v_ashrrev_i32_e32 v22, 3, v20
	s_cselect_b32 s4, 0, 0xfff
	v_lshlrev_b32_e32 v20, 3, v20
	s_add_i32 s30, s1, s4
	v_add_u32_e32 v21, s31, v22
	v_and_b32_e32 v23, 56, v20
	v_mul_lo_u32 v22, v22, s39
	v_or_b32_e32 v20, s35, v23
	v_add_u32_e32 v22, s30, v22
	v_or_b32_e32 v20, s0, v20
	v_mul_u32_u24_e32 v22, 0x300, v22
	v_mad_u32_u24 v20, v21, s63, v20
	v_or3_b32 v22, v22, s37, v23
	v_ashrrev_i32_e32 v21, 31, v20
	v_ashrrev_i32_e32 v23, 31, v22
	v_lshl_add_u64 v[20:21], v[20:21], 1, s[82:83]
	v_lshl_add_u64 v[32:33], v[22:23], 1, s[84:85]
	global_load_dwordx4 v[20:23], v[20:21], off nt
	s_nop 0
	global_load_dwordx4 v[24:27], v[32:33], off nt
	global_load_dwordx4 v[28:31], v[32:33], off offset:512 nt
	s_nop 0
	global_load_dwordx4 v[32:35], v[32:33], off offset:1024 nt
	s_and_saveexec_b64 s[4:5], s[6:7]
	s_cbranch_execz .LBB0_425
	v_add_u32_e32 v44, s31, v68
	v_lshl_add_u32 v44, v44, 4, v59
	v_mov_b32_e32 v45, v181
	v_lshl_add_u64 v[44:45], v[44:45], 2, s[86:87]
	global_load_dword v56, v[44:45], off nt
	v_add_u32_e32 v44, s30, v54
	v_lshl_add_u32 v44, v44, 4, v89
	v_mov_b32_e32 v45, v181
	v_lshl_add_u64 v[44:45], v[44:45], 2, s[86:87]
	global_load_dword v57, v[44:45], off nt

.LBB0_436:
	v_add_u32_e32 v105, s34, v85
	v_cvt_pk_bf16_f32 v48, v48, v49
	v_cvt_pk_bf16_f32 v49, v50, v51
	v_lshl_or_b32 v50, v105, 10, v52
	v_mov_b32_e32 v51, v53
	v_lshl_add_u64 v[50:51], v[50:51], 1, s[28:29]
	global_store_dwordx2 v[50:51], v[48:49], off offset:1024
	v_add_u32_e32 v48, s34, v86
	v_cvt_pk_bf16_f32 v44, v44, v45
	v_cvt_pk_bf16_f32 v45, v46, v47
	v_lshl_or_b32 v46, v48, 10, v52
	v_mov_b32_e32 v47, v53
	v_lshl_add_u64 v[46:47], v[46:47], 1, s[28:29]
	global_store_dwordx2 v[46:47], v[44:45], off offset:1024
	v_mov_b32_e32 v44, v68
	s_waitcnt vmcnt(5)
	v_lshlrev_b32_e32 v108, 16, v12
	v_ashrrev_i32_e32 v45, 3, v44
	v_lshlrev_b32_e32 v44, 4, v44
	v_mul_lo_u32 v105, v45, s61
	v_and_b32_e32 v116, 0x70, v44
	v_add3_u32 v117, 0, v105, v116
	v_lshl_add_u32 v44, v45, 2, 0
	ds_write_b128 v117, v[4:7]
	v_add_u32_e32 v44, 0x1fa00, v44
	ds_read_b32 v118, v44
	v_and_b32_e32 v109, 0xffff0000, v12
	v_and_b32_e32 v45, 0xffff0000, v8
	v_lshlrev_b32_e32 v110, 16, v13
	v_and_b32_e32 v111, 0xffff0000, v13
	s_waitcnt lgkmcnt(0)
	v_mul_f32_e32 v44, 0x3fb8aa3b, v118
	v_exp_f32_e32 v106, v44
	v_lshlrev_b32_e32 v44, 16, v8
	v_lshlrev_b32_e32 v114, 16, v11
	v_and_b32_e32 v115, 0xffff0000, v11
	v_pk_mul_f32 v[46:47], v[106:107], v[108:109] op_sel_hi:[0,1]
	v_cvt_pk_bf16_f32 v48, v46, v47
	v_lshlrev_b32_e32 v46, 16, v9
	v_and_b32_e32 v47, 0xffff0000, v9
	v_pk_mul_f32 v[44:45], v[106:107], v[44:45] op_sel_hi:[0,1]
	v_pk_mul_f32 v[46:47], v[106:107], v[46:47] op_sel_hi:[0,1]
	v_cvt_pk_bf16_f32 v44, v44, v45
	v_cvt_pk_bf16_f32 v45, v46, v47
	v_pk_mul_f32 v[46:47], v[106:107], v[110:111] op_sel_hi:[0,1]
	v_cvt_pk_bf16_f32 v49, v46, v47
	v_lshlrev_b32_e32 v46, 16, v10
	v_and_b32_e32 v47, 0xffff0000, v10
	v_pk_mul_f32 v[46:47], v[106:107], v[46:47] op_sel_hi:[0,1]
	v_pk_mul_f32 v[114:115], v[106:107], v[114:115] op_sel_hi:[0,1]
	v_cvt_pk_bf16_f32 v46, v46, v47
	v_lshlrev_b32_e32 v112, 16, v14
	v_and_b32_e32 v113, 0xffff0000, v14
	v_cvt_pk_bf16_f32 v47, v114, v115
	v_lshlrev_b32_e32 v114, 16, v15
	v_and_b32_e32 v115, 0xffff0000, v15
	v_pk_mul_f32 v[50:51], v[106:107], v[112:113] op_sel_hi:[0,1]
	v_pk_mul_f32 v[106:107], v[106:107], v[114:115] op_sel_hi:[0,1]
	v_readlane_b32 s4, v255, 4
	v_cvt_pk_bf16_f32 v50, v50, v51
	v_cvt_pk_bf16_f32 v51, v106, v107
	v_add3_u32 v106, s4, v105, v116
	ds_write_b128 v106, v[44:47]
	ds_write_b128 v117, v[48:51] offset:18432
	v_add3_u32 v44, s40, v105, v116
	ds_write_b128 v44, v[8:11]
	v_add3_u32 v44, s41, v105, v116
	ds_write_b128 v44, v[12:15]
	s_waitcnt vmcnt(4)
	ds_write_b128 v117, v[16:19] offset:46080
	v_mov_b32_e32 v44, s72
	ds_read_b32 v44, v44
	v_readlane_b32 s4, v255, 6
	s_cmp_gt_u32 s45, 64
	s_waitcnt lgkmcnt(0)
	v_sub_f32_e32 v44, v44, v118
	v_mul_f32_e32 v44, 0x3fb8aa3b, v44
	v_exp_f32_e32 v48, v44
	s_nop 0
	v_pk_mul_f32 v[44:45], v[48:49], v[108:109] op_sel_hi:[0,1]
	v_pk_mul_f32 v[46:47], v[48:49], v[110:111] op_sel_hi:[0,1]
	v_cvt_pk_bf16_f32 v44, v44, v45
	v_cvt_pk_bf16_f32 v45, v46, v47
	v_pk_mul_f32 v[46:47], v[48:49], v[112:113] op_sel_hi:[0,1]
	v_pk_mul_f32 v[48:49], v[48:49], v[114:115] op_sel_hi:[0,1]
	v_cvt_pk_bf16_f32 v46, v46, v47
	v_cvt_pk_bf16_f32 v47, v48, v49
	v_add3_u32 v48, s4, v105, v116
	ds_write_b128 v48, v[44:47]
	s_waitcnt lgkmcnt(0)
	s_barrier
	s_cbranch_scc1 .Lgdn_skipA
	s_and_b64 s[4:5], s[26:27], exec
	s_cselect_b32 s4, s43, s44
	s_lshl_b32 s35, s4, 6
	s_add_i32 s35, s35, s2
	s_add_i32 s34, s33, 64
	v_mov_b32_e32 v4, v68
	s_and_b64 s[4:5], s[26:27], exec
	s_cselect_b32 s34, s42, s34
	v_ashrrev_i32_e32 v6, 3, v4
	s_add_i32 s34, s34, s1
	v_add_u32_e32 v5, s35, v6
	v_lshlrev_b32_e32 v4, 3, v4
	v_mul_lo_u32 v6, v6, s39
	v_and_b32_e32 v7, 56, v4
	v_add_u32_e32 v6, s34, v6
	v_or_b32_e32 v4, s0, v7
	v_mul_u32_u24_e32 v6, 0x300, v6
	v_mad_u32_u24 v4, v5, s63, v4
	v_or3_b32 v6, v6, s37, v7
	v_ashrrev_i32_e32 v5, 31, v4
	v_ashrrev_i32_e32 v7, 31, v6
	v_lshl_add_u64 v[4:5], v[4:5], 1, s[82:83]
	v_lshl_add_u64 v[16:17], v[6:7], 1, s[84:85]
	global_load_dwordx4 v[4:7], v[4:5], off nt
	s_nop 0
	global_load_dwordx4 v[8:11], v[16:17], off nt
	global_load_dwordx4 v[12:15], v[16:17], off offset:512 nt
	s_nop 0
	global_load_dwordx4 v[16:19], v[16:17], off offset:1024 nt
	s_and_saveexec_b64 s[4:5], s[6:7]
	s_cbranch_execz .LBB0_439
	v_add_u32_e32 v44, s35, v68
	v_lshl_add_u32 v180, v44, 4, v59
	v_lshl_add_u64 v[44:45], v[180:181], 2, s[86:87]
	global_load_dword v55, v[44:45], off nt
	v_add_u32_e32 v44, s34, v54
	v_lshl_add_u32 v180, v44, 4, v89
	v_lshl_add_u64 v[44:45], v[180:181], 2, s[86:87]
	global_load_dword v58, v[44:45], off nt

.LBB0_450:
	s_cmp_gt_u32 s48, 64
	s_waitcnt lgkmcnt(0)
	s_barrier
	s_cbranch_scc1 .Lgdn_skipB
	s_add_i32 s30, s43, 1
	s_add_i32 s31, s44, -1
	s_and_b64 s[4:5], s[26:27], exec
	s_cselect_b32 s4, s30, s31
	s_lshl_b32 s31, s4, 6
	s_add_i32 s31, s31, s2
	s_waitcnt vmcnt(7)
	v_mov_b32_e32 v20, v68
	s_and_b64 s[4:5], s[26:27], exec
	s_cselect_b32 s30, s47, s33
	v_ashrrev_i32_e32 v22, 3, v20
	s_add_i32 s30, s30, s1
	v_add_u32_e32 v21, s31, v22
	v_lshlrev_b32_e32 v20, 3, v20
	v_mul_lo_u32 v22, v22, s39
	v_and_b32_e32 v23, 56, v20
	v_add_u32_e32 v22, s30, v22
	v_or_b32_e32 v20, s0, v23
	v_mul_u32_u24_e32 v22, 0x300, v22
	v_mad_u32_u24 v20, v21, s63, v20
	v_or3_b32 v22, v22, s37, v23
	v_ashrrev_i32_e32 v21, 31, v20
	v_ashrrev_i32_e32 v23, 31, v22
	v_lshl_add_u64 v[20:21], v[20:21], 1, s[82:83]
	s_waitcnt vmcnt(4)
	v_lshl_add_u64 v[32:33], v[22:23], 1, s[84:85]
	global_load_dwordx4 v[20:23], v[20:21], off nt
	s_nop 0
	global_load_dwordx4 v[24:27], v[32:33], off nt
	global_load_dwordx4 v[28:31], v[32:33], off offset:512 nt
	s_nop 0
	global_load_dwordx4 v[32:35], v[32:33], off offset:1024 nt
	s_and_saveexec_b64 s[4:5], s[6:7]
	s_cbranch_execz .LBB0_426
	v_add_u32_e32 v44, s31, v68
	v_lshl_add_u32 v180, v44, 4, v59
	v_lshl_add_u64 v[44:45], v[180:181], 2, s[86:87]
	global_load_dword v56, v[44:45], off nt
	v_add_u32_e32 v44, s30, v54
	v_lshl_add_u32 v180, v44, 4, v89
	v_lshl_add_u64 v[44:45], v[180:181], 2, s[86:87]
	global_load_dword v57, v[44:45], off nt
	s_branch .LBB0_426

.LBB0_467:
	s_or_b64 exec, exec, s[6:7]
	v_readlane_b32 s5, v255, 33
	s_lshr_b32 s2, s5, 3
	s_lshl_b32 s5, s5, 5
	s_ashr_i32 s15, s1, 6
	s_and_b32 s0, s65, 1
	s_bfe_i32 s4, s65, 0x10000
	s_and_b32 s14, s5, 0xc0
	s_cmp_lt_i32 s15, 6
	s_cselect_b32 s5, 2, -2
	s_cmp_gt_i32 s15, 3
	s_cselect_b32 s16, s5, 0
	s_add_i32 s16, s16, s15
	s_lshl_b32 s44, s2, 8
	s_and_b32 s4, s4, 0xff
	s_waitcnt vmcnt(5)
	v_mov_b32_e32 v4, v68
	s_or_b32 s5, s4, s44
	s_lshl_b32 s70, s16, 3
	s_lshl_b32 s48, s14, 1
	s_lshl_b32 s4, s0, 9
	s_cmp_eq_u32 s0, 0
	v_lshrrev_b32_e32 v5, 3, v4
	v_and_or_b32 v5, v5, 7, s70
	v_sub_u32_e32 v6, 0, v5
	s_cselect_b64 s[6:7], -1, 0
	v_cndmask_b32_e64 v5, v6, v5, s[6:7]
	v_add_u32_e32 v5, s5, v5
	v_mul_u32_u24_e32 v5, 0xe00, v5
	v_lshlrev_b32_e32 v4, 3, v4
	v_and_or_b32 v4, v4, 56, v5
	v_ashrrev_i32_e32 v5, 31, v4
	v_lshl_add_u64 v[4:5], v[4:5], 1, s[82:83]
	s_waitcnt vmcnt(3)
	v_lshl_add_u64 v[12:13], v[4:5], 0, s[48:49]
	s_mov_b32 s5, s49
	v_lshl_add_u64 v[4:5], v[12:13], 0, s[4:5]
	s_waitcnt vmcnt(2)
	v_mov_b32_e32 v16, v68
	global_load_dwordx4 v[4:7], v[4:5], off offset:1536 nt
	s_nop 0
	global_load_dwordx4 v[8:11], v[12:13], off nt
	s_nop 0
	global_load_dwordx4 v[12:15], v[12:13], off offset:512 nt
	s_and_b64 s[8:9], s[6:7], exec
	v_lshrrev_b32_e32 v17, 3, v16
	v_and_or_b32 v17, v17, 7, s70
	s_cselect_b32 s8, 64, 0xbf
	v_sub_u32_e32 v18, 0, v17
	s_or_b32 s8, s8, s44
	v_cndmask_b32_e64 v17, v18, v17, s[6:7]
	v_add_u32_e32 v17, s8, v17
	v_mul_u32_u24_e32 v17, 0xe00, v17
	v_lshlrev_b32_e32 v16, 3, v16
	v_and_or_b32 v16, v16, 56, v17
	v_ashrrev_i32_e32 v17, 31, v16
	v_lshl_add_u64 v[16:17], v[16:17], 1, s[82:83]
	v_lshl_add_u64 v[20:21], v[16:17], 0, s[48:49]
	v_lshl_add_u64 v[22:23], v[20:21], 0, s[4:5]
	global_load_dwordx4 v[16:19], v[20:21], off nt
	global_load_dwordx4 v[24:27], v[20:21], off offset:512 nt
	s_nop 0
	global_load_dwordx4 v[20:23], v[22:23], off offset:1536 nt
	s_waitcnt vmcnt(7)
	v_mov_b32_e32 v29, v68
	s_add_i32 s17, s15, -2
	v_lshrrev_b32_e32 v30, 3, v29
	v_lshlrev_b32_e32 v29, 4, v29
	v_and_or_b32 v30, v30, 7, s70
	s_waitcnt vmcnt(6)
	v_and_b32_e32 v32, 63, v68
	v_and_b32_e32 v29, 0x70, v29
	v_mul_lo_u32 v30, v30, s61
	v_readlane_b32 s4, v255, 7
	s_cmp_lt_u32 s17, 16
	v_and_b32_e32 v28, 15, v68
	v_add3_u32 v29, s4, v30, v29
	s_cselect_b64 s[88:89], -1, 0
	v_lshrrev_b32_e32 v30, 1, v68
	v_bfe_u32 v31, v68, 2, 2
	v_lshlrev_b32_e32 v33, 3, v32
	s_and_b64 vcc, exec, s[88:89]
	v_and_b32_e32 v64, 48, v68
	v_and_or_b32 v30, v30, 24, v31
	v_and_b32_e32 v65, 24, v33
	s_waitcnt vmcnt(5)
	ds_write_b128 v29, v[4:7]
	v_lshlrev_b32_e32 v29, 8, v28
	s_waitcnt lgkmcnt(0)
	s_barrier
	s_cbranch_vccz .LBB0_471
	v_readlane_b32 s8, v255, 7
	s_and_b32 s4, s17, 3
	s_lshr_b32 s5, s17, 2
	v_mov_b32_e32 v31, s8
	v_mad_u32_u24 v31, v30, s61, v31
	s_lshl_b32 s8, s4, 5
	v_add3_u32 v33, v31, s8, v65
	v_lshl_or_b32 v38, s5, 4, v28
	ds_read_b64_tr_b16 v[34:35], v33
	ds_read_b64_tr_b16 v[36:37], v33 offset:576
	v_mul_lo_u32 v38, v38, s61
	v_add3_u32 v46, s58, v38, v64
	ds_read_b128 v[38:41], v46
	ds_read_b64_tr_b16 v[42:43], v33 offset:4608
	ds_read_b64_tr_b16 v[44:45], v33 offset:5184
	s_waitcnt lgkmcnt(2)
	v_mfma_f32_16x16x32_bf16 v[34:37], v[34:37], v[38:41], 0
	ds_read_b128 v[38:41], v46 offset:64
	s_lshl_b32 s5, s5, 12
	s_add_i32 s5, s5, 0
	s_waitcnt lgkmcnt(0)
	v_mfma_f32_16x16x32_bf16 v[34:37], v[42:45], v[38:41], v[34:37]
	s_lshl_b32 s4, s4, 6
	s_add_i32 s4, s5, s4
	s_add_i32 s4, s4, 0x15600
	v_add3_u32 v33, s4, v29, v64
	s_cmp_gt_u32 s15, 11
	s_nop 2
	ds_write_b128 v33, v[34:37]
	s_cbranch_scc1 .LBB0_471
	s_add_i32 s4, s15, 4
	s_bfe_u32 s5, s1, 0x20006
	s_lshr_b32 s4, s4, 2
	s_lshl_b32 s8, s5, 5
	v_add3_u32 v33, v31, s8, v65
	v_lshl_or_b32 v38, s4, 4, v28
	ds_read_b64_tr_b16 v[34:35], v33
	ds_read_b64_tr_b16 v[36:37], v33 offset:576
	v_mul_lo_u32 v38, v38, s61
	v_add3_u32 v46, s58, v38, v64
	ds_read_b128 v[38:41], v46
	ds_read_b64_tr_b16 v[42:43], v33 offset:4608
	ds_read_b64_tr_b16 v[44:45], v33 offset:5184
	s_waitcnt lgkmcnt(2)
	v_mfma_f32_16x16x32_bf16 v[34:37], v[34:37], v[38:41], 0
	ds_read_b128 v[38:41], v46 offset:64
	s_lshl_b32 s4, s4, 12
	s_add_i32 s4, s4, 0
	s_waitcnt lgkmcnt(0)
	v_mfma_f32_16x16x32_bf16 v[34:37], v[42:45], v[38:41], v[34:37]
	s_lshl_b32 s5, s5, 6
	s_add_i32 s4, s4, s5
	s_add_i32 s4, s4, 0x15600
	v_add3_u32 v33, s4, v29, v64
	s_cmp_gt_u32 s15, 5
	s_nop 2
	ds_write_b128 v33, v[34:37]
	s_cbranch_scc1 .LBB0_471
	s_add_i32 s4, s15, 10
	s_and_b32 s5, s4, 3
	s_lshr_b32 s4, s4, 2
	s_lshl_b32 s8, s5, 5
	v_add3_u32 v31, v31, s8, v65
	v_lshl_or_b32 v33, s4, 4, v28
	ds_read_b64_tr_b16 v[34:35], v31
	ds_read_b64_tr_b16 v[36:37], v31 offset:576
	v_mul_lo_u32 v33, v33, s61
	v_add3_u32 v33, s58, v33, v64
	ds_read_b128 v[38:41], v33
	ds_read_b64_tr_b16 v[42:43], v31 offset:4608
	ds_read_b64_tr_b16 v[44:45], v31 offset:5184
	s_waitcnt lgkmcnt(2)
	v_mfma_f32_16x16x32_bf16 v[34:37], v[34:37], v[38:41], 0
	ds_read_b128 v[38:41], v33 offset:64
	s_lshl_b32 s4, s4, 12
	s_add_i32 s4, s4, 0
	s_waitcnt lgkmcnt(0)
	v_mfma_f32_16x16x32_bf16 v[34:37], v[42:45], v[38:41], v[34:37]
	s_lshl_b32 s5, s5, 6
	s_add_i32 s4, s4, s5
	s_add_i32 s4, s4, 0x15600
	v_add3_u32 v31, s4, v29, v64
	s_nop 3
	ds_write_b128 v31, v[34:37]

.LBB0_488:
	v_mov_b32_e32 v36, v68
	s_cmpk_lt_u32 s47, 0x42
	v_lshrrev_b32_e32 v37, 3, v36
	v_and_or_b32 v37, v37, 7, s70
	v_lshlrev_b32_e32 v36, 4, v36
	s_cselect_b64 s[54:55], -1, 0
	s_cmpk_gt_u32 s47, 0x41
	v_mul_lo_u32 v37, v37, s61
	v_and_b32_e32 v36, 0x70, v36
	v_readlane_b32 s4, v255, 7
	s_cselect_b64 s[60:61], -1, 0
	s_movk_i32 s72, 0x90
	v_add3_u32 v36, s4, v37, v36
	s_and_b64 vcc, exec, s[60:61]
	s_waitcnt vmcnt(4)
	ds_write_b128 v36, v[20:23]
	s_waitcnt lgkmcnt(0)
	s_barrier
	s_cbranch_vccnz .Lhg_skipA
	s_lshl_b32 s4, s47, 6
	s_add_i32 s36, s4, 0xffffff80
	s_sub_i32 s37, 0x107f, s4
	v_mov_b32_e32 v4, v68
	s_and_b64 s[4:5], s[6:7], exec
	s_cselect_b32 s4, s36, s37
	v_lshrrev_b32_e32 v5, 3, v4
	s_add_i32 s4, s4, s76
	v_and_or_b32 v5, v5, 7, s70
	s_cmp_eq_u32 s47, 0
	v_sub_u32_e32 v6, 0, v5
	s_cselect_b32 s4, s2, s4
	v_cndmask_b32_e64 v5, v6, v5, s[6:7]
	v_add_u32_e32 v5, s4, v5
	v_mul_u32_u24_e32 v5, 0xe00, v5
	v_lshlrev_b32_e32 v4, 3, v4
	v_and_or_b32 v4, v4, 56, v5
	v_ashrrev_i32_e32 v5, 31, v4
	v_lshl_add_u64 v[12:13], v[4:5], 1, s[58:59]
	s_lshl_b32 s48, s73, 1
	v_lshl_add_u64 v[4:5], v[12:13], 0, s[48:49]
	global_load_dwordx4 v[4:7], v[4:5], off offset:1536 nt
	s_nop 0
	global_load_dwordx4 v[8:11], v[12:13], off nt
	s_nop 0
	global_load_dwordx4 v[12:15], v[12:13], off offset:512 nt

.LBB0_517:
	s_andn2_b64 vcc, exec, s[54:55]
	s_waitcnt lgkmcnt(0)
	s_barrier
	s_cbranch_vccnz .Lhg_skipB
	s_lshl_b32 s4, s40, 6
	s_add_i32 s41, s4, 0xffffff80
	s_sub_i32 s48, 0x107f, s4
	v_mov_b32_e32 v16, v68
	s_and_b64 s[4:5], s[6:7], exec
	s_cselect_b32 s4, s41, s48
	v_lshrrev_b32_e32 v17, 3, v16
	s_add_i32 s4, s4, s76
	v_and_or_b32 v17, v17, 7, s70
	s_cmp_eq_u32 s47, 0
	v_sub_u32_e32 v18, 0, v17
	s_cselect_b32 s4, s74, s4
	v_cndmask_b32_e64 v17, v18, v17, s[6:7]
	v_add_u32_e32 v17, s4, v17
	v_mul_u32_u24_e32 v17, 0xe00, v17
	v_lshlrev_b32_e32 v16, 3, v16
	v_and_or_b32 v16, v16, 56, v17
	v_ashrrev_i32_e32 v17, 31, v16
	v_lshl_add_u64 v[24:25], v[16:17], 1, s[58:59]
	s_lshl_b32 s48, s73, 1
	v_lshl_add_u64 v[16:17], v[24:25], 0, s[48:49]
	global_load_dwordx4 v[20:23], v[16:17], off offset:1536 nt
	s_nop 0
	global_load_dwordx4 v[16:19], v[24:25], off nt
	s_nop 0
	global_load_dwordx4 v[24:27], v[24:25], off offset:512 nt

.LBB0_540:
	s_lshl_b32 s4, s12, 2
	v_add_u32_e32 v36, s15, v68
	s_or_b32 s4, s11, s4
	v_lshl_or_b32 v180, v36, 4, s4
	v_lshl_add_u64 v[36:37], v[180:181], 2, s[86:87]
	global_load_dword v56, v[36:37], off nt
	v_add_lshl_u32 v36, s14, v54, 4
	v_or3_b32 v180, v36, s4, 8
	v_lshl_add_u64 v[36:37], v[180:181], 2, s[86:87]
	global_load_dword v57, v[36:37], off nt
	v_mov_b32_e32 v59, s4
	s_or_b64 exec, exec, s[8:9]
	v_lshl_add_u32 v60, v68, 2, s58
	s_and_saveexec_b64 s[4:5], s[6:7]
	s_cbranch_execnz .LBB0_414
	s_branch .LBB0_415

.LBB0_542:
	s_and_b64 vcc, exec, s[4:5]
	s_cbranch_vccz .LBB0_342
	s_and_b32 s16, s65, 1
	s_load_dwordx2 s[4:5], s[80:81], 0x58
	s_lshl_b32 s1, s16, 2
	v_readlane_b32 s2, v255, 30
	s_bfe_u32 s0, s65, 0x20001
	s_or_b32 s1, s1, s2
	s_or_b32 s6, s1, s0
	s_ashr_i32 s7, s6, 31
	s_lshl_b64 s[6:7], s[6:7], 2
	s_waitcnt lgkmcnt(0)
	s_add_u32 s4, s4, s6
	s_addc_u32 s5, s5, s7
	global_load_dword v4, v181, s[4:5] nt
	s_movk_i32 s2, 0x6c0
	v_readfirstlane_b32 s1, v68
	v_cmp_gt_i32_e32 vcc, s2, v68
	s_and_saveexec_b64 s[6:7], vcc
	s_movk_i32 s2, 0x4bf
	s_cbranch_execz .LBB0_546
	v_readlane_b32 s4, v255, 11
	s_waitcnt vmcnt(6)
	v_add_u32_e32 v5, 0xfffffe00, v68
	v_lshl_add_u32 v6, v68, 4, s4
	s_mov_b64 s[4:5], 0

.LBB0_546:
	s_or_b64 exec, exec, s[6:7]
	s_waitcnt vmcnt(0)
	v_mul_f32_e32 v5, 0xbfb8aa3b, v4
	v_rndne_f32_e32 v6, v5
	s_mov_b32 s2, 0xbfb8aa3b
	v_sub_f32_e32 v7, v5, v6
	v_fma_f32 v5, v4, s2, -v5
	v_fmac_f32_e32 v5, 0xb2a5705f, v4
	v_add_f32_e32 v5, v7, v5
	v_cvt_i32_f32_e32 v6, v6
	v_exp_f32_e32 v5, v5
	s_mov_b32 s2, 0x42ce8ed0
	v_cmp_nlt_f32_e32 vcc, s2, v4
	s_mov_b32 s2, 0xc2b17218
	v_ldexp_f32 v5, v5, v6
	v_cndmask_b32_e32 v5, 0, v5, vcc
	v_cmp_ngt_f32_e32 vcc, s2, v4
	s_mov_b32 s2, 0x800000
	s_lshl_b32 s0, s0, 6
	v_cndmask_b32_e32 v4, v249, v5, vcc
	v_add_f32_e32 v4, 1.0, v4
	v_div_scale_f32 v5, s[4:5], v4, v4, 1.0
	v_rcp_f32_e32 v6, v5
	s_ashr_i32 s4, s1, 6
	v_readlane_b32 s1, v255, 33
	s_lshr_b32 s1, s1, 3
	v_fma_f32 v7, -v5, v6, 1.0
	v_fmac_f32_e32 v6, v7, v6
	v_div_scale_f32 v7, vcc, 1.0, v4, 1.0
	v_mul_f32_e32 v8, v7, v6
	v_fma_f32 v9, -v5, v8, v7
	v_fmac_f32_e32 v8, v9, v6
	v_fma_f32 v5, -v5, v8, v7
	v_div_fmas_f32 v5, v5, v6, v8
	v_div_fixup_f32 v4, v5, v4, 1.0
	v_cmp_gt_f32_e32 vcc, s2, v4
	s_and_b64 s[6:7], vcc, exec
	s_cselect_b32 s2, 32, 0
	v_ldexp_f32 v4, v4, s2
	v_log_f32_e32 v4, v4
	v_mov_b32_e32 v5, 0x42000000
	v_cndmask_b32_e32 v5, 0, v5, vcc
	s_mov_b32 s2, 0xc2fc0000
	v_sub_f32_e32 v29, v4, v5
	v_mul_f32_e32 v4, 0x42800000, v29
	v_cmp_gt_f32_e32 vcc, s2, v4
	s_and_b64 s[6:7], vcc, exec
	s_cselect_b32 s14, 0xffffffc0, 0
	s_add_i32 s2, s4, -8
	s_cmp_gt_i32 s4, 9
	s_cselect_b32 s2, s2, s4
	s_cmp_gt_i32 s2, 0
	v_mov_b32_e32 v4, 0x42800000
	s_cselect_b64 s[6:7], -1, 0
	v_cndmask_b32_e32 v12, 0, v4, vcc
	v_cndmask_b32_e64 v4, 0, 1, s[6:7]
	s_cmp_lt_i32 s2, 3
	v_readfirstlane_b32 s5, v4
	s_cselect_b32 s5, s5, 2
	s_cmp_lt_i32 s2, 6
	s_cselect_b32 s22, s5, 3
	s_add_i32 s5, s22, 1
	s_mul_i32 s5, s5, s22
	s_lshr_b32 s5, s5, 1
	s_sub_i32 s20, s2, s5
	s_sub_i32 s15, s22, s20
	s_add_i32 s2, s4, 8
	s_cmp_gt_i32 s4, 1
	s_cselect_b64 s[6:7], -1, 0
	s_and_b64 s[8:9], s[6:7], exec
	s_cselect_b32 s2, s4, s2
	s_cmp_gt_i32 s2, 0
	s_cselect_b64 s[8:9], -1, 0
	v_cndmask_b32_e64 v4, 0, 1, s[8:9]
	s_cmp_lt_i32 s2, 3
	v_readfirstlane_b32 s5, v4
	s_cselect_b32 s5, s5, 2
	s_cmp_lt_i32 s2, 6
	s_cselect_b32 s21, s5, 3
	s_add_i32 s5, s21, 1
	s_mul_i32 s5, s5, s21
	s_lshr_b32 s5, s5, 1
	s_sub_i32 s18, s2, s5
	s_sub_i32 s23, s21, s18
	s_lshl_b32 s2, s1, 8
	s_cmp_eq_u32 s16, 0
	s_cselect_b64 s[8:9], -1, 0
	s_and_b64 s[10:11], s[8:9], exec
	v_ashrrev_i32_e32 v31, 3, v68
	s_cselect_b32 s5, 0, 0xff
	s_cselect_b32 s19, 1, -1
	s_cselect_b32 s17, 64, 0xbf
	s_or_b32 s5, s5, s2
	v_mul_lo_u32 v60, s19, v31
	v_and_b32_e32 v40, 7, v68
	v_add_u32_e32 v4, s5, v60
	v_mul_u32_u24_e32 v4, 0xe00, v4
	v_lshlrev_b32_e32 v77, 3, v40
	v_or3_b32 v4, v4, s0, v77
	v_ashrrev_i32_e32 v5, 31, v4
	v_lshl_add_u64 v[8:9], v[4:5], 1, s[82:83]
	global_load_dwordx4 v[4:7], v[8:9], off offset:2560 nt
	s_nop 0
	global_load_dwordx4 v[8:11], v[8:9], off offset:3072 nt
	v_fmac_f32_e32 v12, 0x42800000, v29
	v_exp_f32_e32 v16, v12
	v_and_b32_e32 v58, 31, v68
	v_ashrrev_i32_e32 v41, 5, v68
	s_lshl_b32 s24, s19, 1
	v_mov_b32_e32 v12, s5
	v_mad_i32_i24 v12, s24, v58, v12
	v_lshl_add_u32 v61, v41, 2, s0
	v_mad_u32_u24 v12, v12, s63, v61
	s_mul_i32 s10, s19, 0xe00
	v_ashrrev_i32_e32 v13, 31, v12
	s_ashr_i32 s11, s10, 31
	v_lshl_add_u64 v[12:13], v[12:13], 1, s[82:83]
	s_lshl_b64 s[12:13], s[10:11], 1
	v_lshl_add_u64 v[14:15], v[12:13], 0, s[12:13]
	global_load_dwordx2 v[22:23], v[12:13], off offset:3584 nt
	global_load_dwordx2 v[24:25], v[14:15], off offset:3584 nt
	global_load_dwordx2 v[26:27], v[14:15], off offset:3072 nt
	global_load_dwordx2 v[34:35], v[12:13], off offset:3072 nt
	v_add_u32_e32 v17, 1, v31
	v_cvt_f32_i32_e32 v12, v17
	v_and_b32_e32 v21, 15, v68
	v_bfe_u32 v59, v68, 4, 2
	v_lshlrev_b32_e32 v20, 2, v59
	v_lshl_or_b32 v65, s15, 4, v21
	v_or_b32_e32 v66, 1, v20
	v_sub_u32_e32 v67, v65, v20
	v_mul_f32_e32 v12, v29, v12
	v_lshlrev_b32_e32 v13, 1, v58
	v_cvt_f32_u32_e32 v15, v67
	v_sub_u32_e32 v68, v65, v66
	s_or_b32 s17, s17, s2
	v_ldexp_f32 v28, v16, s14
	v_xor_b32_e32 v14, 63, v13
	v_xor_b32_e32 v13, 62, v13
	v_cvt_f32_u32_e32 v16, v68
	v_exp_f32_e32 v30, v12
	v_add_u32_e32 v12, s17, v60
	v_mov_b32_e32 v36, s17
	v_cvt_f32_ubyte0_e32 v13, v13
	v_mul_u32_u24_e32 v12, 0xe00, v12
	v_mad_i32_i24 v36, s24, v58, v36
	v_mul_f32_e32 v13, v29, v13
	v_or3_b32 v12, v12, s0, v77
	v_mad_u32_u24 v36, v36, s63, v61
	v_cvt_f32_ubyte0_e32 v14, v14
	v_mul_f32_e32 v15, v29, v15
	v_exp_f32_e32 v33, v13
	v_ashrrev_i32_e32 v13, 31, v12
	v_ashrrev_i32_e32 v37, 31, v36
	v_mul_f32_e32 v14, v29, v14
	v_exp_f32_e32 v69, v15
	v_mul_f32_e32 v15, v29, v16
	v_lshl_add_u64 v[16:17], v[12:13], 1, s[82:83]
	v_lshl_add_u64 v[36:37], v[36:37], 1, s[82:83]
	v_mul_lo_u32 v31, v31, s61
	v_exp_f32_e32 v70, v15
	v_exp_f32_e32 v32, v14
	global_load_dwordx4 v[12:15], v[16:17], off offset:2560 nt
	s_nop 0
	global_load_dwordx4 v[16:19], v[16:17], off offset:3072 nt
	v_lshl_add_u64 v[38:39], v[36:37], 0, s[12:13]
	global_load_dwordx2 v[42:43], v[36:37], off offset:3584 nt
	global_load_dwordx2 v[52:53], v[38:39], off offset:3584 nt
	global_load_dwordx2 v[56:57], v[38:39], off offset:3072 nt
	global_load_dwordx2 v[54:55], v[36:37], off offset:3072 nt
	v_add_u32_e32 v31, 0, v31
	v_lshlrev_b32_e32 v36, 4, v40
	s_movk_i32 s14, 0x240
	v_add_u32_e32 v62, v31, v36
	v_mul_lo_u32 v31, v41, s14
	v_add_u32_e32 v31, 0, v31
	v_lshlrev_b32_e32 v36, 2, v58
	s_waitcnt lgkmcnt(0)
	s_barrier
	v_add_u32_e32 v31, v31, v36
	s_waitcnt vmcnt(11)
	ds_write_b128 v62, v[4:7]
	s_waitcnt vmcnt(10)
	ds_write_b128 v62, v[8:11] offset:9216
	v_lshlrev_b32_e32 v8, 16, v4
	v_and_b32_e32 v9, 0xffff0000, v4
	v_pk_mul_f32 v[8:9], v[30:31], v[8:9] op_sel_hi:[0,1]
	v_cvt_pk_bf16_f32 v4, v8, v9
	v_lshlrev_b32_e32 v8, 16, v5
	v_and_b32_e32 v9, 0xffff0000, v5
	v_pk_mul_f32 v[8:9], v[30:31], v[8:9] op_sel_hi:[0,1]
	v_cvt_pk_bf16_f32 v5, v8, v9
	v_lshlrev_b32_e32 v8, 16, v6
	v_and_b32_e32 v9, 0xffff0000, v6
	v_pk_mul_f32 v[8:9], v[30:31], v[8:9] op_sel_hi:[0,1]
	v_cvt_pk_bf16_f32 v6, v8, v9
	v_lshlrev_b32_e32 v8, 16, v7
	v_and_b32_e32 v9, 0xffff0000, v7
	v_pk_mul_f32 v[8:9], v[30:31], v[8:9] op_sel_hi:[0,1]
	v_cvt_pk_bf16_f32 v7, v8, v9
	ds_write_b128 v62, v[4:7] offset:18432
	s_waitcnt vmcnt(9)
	v_and_b32_e32 v4, 0xffff, v22
	s_waitcnt vmcnt(8)
	v_lshl_or_b32 v6, v24, 16, v4
	s_waitcnt vmcnt(6)
	v_lshlrev_b32_e32 v4, 16, v34
	v_lshlrev_b32_e32 v5, 16, v26
	v_pk_mul_f32 v[4:5], v[32:33], v[4:5]
	v_add_u32_e32 v63, 0x6c00, v31
	v_cvt_pk_bf16_f32 v7, v4, v5
	v_lshrrev_b32_e32 v4, 16, v22
	v_and_or_b32 v4, v24, s60, v4
	ds_write2_b32 v63, v6, v4 offset1:36
	v_and_b32_e32 v5, 0xffff0000, v26
	v_and_b32_e32 v4, 0xffff0000, v34
	v_pk_mul_f32 v[4:5], v[32:33], v[4:5]
	v_add_u32_e32 v64, 0x9000, v31
	v_cvt_pk_bf16_f32 v4, v4, v5
	ds_write2_b32 v64, v7, v4 offset1:36
	v_and_b32_e32 v4, 0xffff, v23
	v_lshl_or_b32 v6, v25, 16, v4
	v_lshlrev_b32_e32 v4, 16, v35
	v_lshlrev_b32_e32 v5, 16, v27
	v_pk_mul_f32 v[4:5], v[32:33], v[4:5]
	s_cmp_lt_i32 s4, 2
	v_cvt_pk_bf16_f32 v7, v4, v5
	v_lshrrev_b32_e32 v4, 16, v23
	v_and_or_b32 v4, v25, s60, v4
	ds_write2_b32 v63, v6, v4 offset0:72 offset1:108
	v_and_b32_e32 v5, 0xffff0000, v27
	v_and_b32_e32 v4, 0xffff0000, v35
	s_cselect_b64 s[14:15], -1, 0
	s_sub_i32 s16, s2, s16
	v_pk_mul_f32 v[4:5], v[32:33], v[4:5]
	s_addk_i32 s16, 0x80
	v_cvt_pk_bf16_f32 v4, v4, v5
	ds_write2_b32 v64, v7, v4 offset0:72 offset1:108
	v_add_u32_e32 v4, s16, v60
	v_mov_b32_e32 v22, s16
	v_mul_u32_u24_e32 v4, 0xe00, v4
	v_mad_i32_i24 v22, s24, v58, v22
	v_or3_b32 v4, v4, v77, s0
	v_mad_u32_u24 v22, v22, s63, v61
	v_ashrrev_i32_e32 v5, 31, v4
	v_ashrrev_i32_e32 v23, 31, v22
	v_lshl_add_u64 v[8:9], v[4:5], 1, s[82:83]
	v_lshl_add_u64 v[22:23], v[22:23], 1, s[82:83]
	s_waitcnt lgkmcnt(0)
	s_barrier
	global_load_dwordx4 v[4:7], v[8:9], off offset:2560 nt
	s_nop 0
	global_load_dwordx4 v[8:11], v[8:9], off offset:3072 nt
	v_lshl_add_u64 v[24:25], v[22:23], 0, s[12:13]
	global_load_dwordx2 v[44:45], v[22:23], off offset:3584 nt
	global_load_dwordx2 v[46:47], v[24:25], off offset:3584 nt
	global_load_dwordx2 v[50:51], v[24:25], off offset:3072 nt
	global_load_dwordx2 v[48:49], v[22:23], off offset:3072 nt
	v_lshl_or_b32 v22, s23, 4, v21
	v_sub_u32_e32 v23, v22, v66
	v_cvt_f32_u32_e32 v25, v23
	v_sub_u32_e32 v24, v22, v20
	v_cvt_f32_u32_e32 v26, v24
	v_cmp_lt_i32_e32 vcc, -1, v68
	v_mul_f32_e32 v25, v29, v25
	v_exp_f32_e32 v25, v25
	v_cndmask_b32_e32 v35, 0, v70, vcc
	v_cmp_lt_i32_e32 vcc, -1, v67
	v_mul_f32_e32 v26, v29, v26
	v_exp_f32_e32 v26, v26
	v_cndmask_b32_e32 v34, 0, v69, vcc
	v_cmp_lt_i32_e32 vcc, -1, v23
	v_or_b32_e32 v23, 3, v20
	v_sub_u32_e32 v27, v65, v23
	v_cndmask_b32_e32 v37, 0, v25, vcc
	v_or_b32_e32 v25, 2, v20
	v_cvt_f32_u32_e32 v38, v27
	v_sub_u32_e32 v31, v65, v25
	v_cvt_f32_u32_e32 v39, v31
	v_cmp_lt_i32_e32 vcc, -1, v24
	v_sub_u32_e32 v23, v22, v23
	v_mul_f32_e32 v24, v29, v38
	v_cndmask_b32_e32 v36, 0, v26, vcc
	v_cmp_lt_i32_e32 vcc, -1, v27
	v_sub_u32_e32 v27, v22, v25
	v_cvt_f32_u32_e32 v22, v23
	v_exp_f32_e32 v24, v24
	v_mul_f32_e32 v26, v29, v39
	v_exp_f32_e32 v26, v26
	v_mul_f32_e32 v22, v29, v22
	v_exp_f32_e32 v22, v22
	v_cndmask_b32_e32 v39, 0, v24, vcc
	v_cvt_f32_u32_e32 v24, v27
	v_cmp_lt_i32_e32 vcc, -1, v31
	v_lshlrev_b32_e32 v79, 4, v59
	v_lshl_add_u32 v78, v59, 3, 0
	v_cndmask_b32_e32 v38, 0, v26, vcc
	v_cmp_lt_i32_e32 vcc, -1, v23
	v_mul_f32_e32 v24, v29, v24
	v_lshl_or_b32 v29, s22, 4, v21
	v_cndmask_b32_e32 v41, 0, v22, vcc
	v_lshl_or_b32 v22, s20, 4, v21
	v_mul_lo_u32 v22, v22, s61
	v_add_u32_e32 v22, 0, v22
	v_mad_u32_u24 v31, v29, s61, 0
	v_add_u32_e32 v65, v22, v79
	v_add_u32_e32 v66, v31, v79
	v_exp_f32_e32 v26, v24
	ds_read_b128 v[22:25], v65 offset:9216
	ds_read_b128 v[68:71], v65 offset:9280
	ds_read_b128 v[72:75], v66
	ds_read_b128 v[80:83], v66 offset:64
	v_cmp_lt_i32_e32 vcc, -1, v27
	s_lshl_b32 s13, s20, 5
	s_lshl_b32 s12, s4, 4
	v_cndmask_b32_e32 v40, 0, v26, vcc
	s_waitcnt lgkmcnt(1)
	v_mfma_f32_16x16x32_bf16 v[24:27], v[22:25], v[72:75], 0
	v_mad_u32_u24 v23, v29, s61, v78
	s_and_b32 s12, s12, 48
	v_mul_i32_i24_e32 v67, s24, v58
	s_waitcnt lgkmcnt(0)
	v_mfma_f32_16x16x32_bf16 v[24:27], v[68:71], v[80:83], v[24:27]
	v_add_u32_e32 v68, s13, v23
	v_lshl_or_b32 v23, s18, 4, v21
	v_mul_lo_u32 v80, v23, s61
	v_or_b32_e32 v22, s12, v21
	s_and_b64 vcc, exec, s[14:15]
	s_nop 2
	v_pk_mul_f32 v[24:25], v[34:35], v[24:25]
	v_pk_mul_f32 v[26:27], v[38:39], v[26:27]
	v_cvt_pk_bf16_f32 v24, v24, v25
	v_cvt_pk_bf16_f32 v25, v26, v27
	v_add3_u32 v29, 0, v80, v79
	v_lshl_or_b32 v81, s21, 4, v21
	ds_write_b64 v68, v[24:25] offset:46080
	s_cbranch_vccz .LBB0_548
	ds_read_b128 v[24:27], v29 offset:9216
	v_mul_u32_u24_e32 v23, 0x90, v81
	v_add3_u32 v31, 0, v23, v79
	ds_read_b128 v[70:73], v31
	ds_read_b128 v[82:85], v29 offset:9280
	s_lshl_b32 s13, s18, 5
	v_add3_u32 v23, v78, v23, s13
	s_waitcnt lgkmcnt(1)
	v_mfma_f32_16x16x32_bf16 v[24:27], v[24:27], v[70:73], 0
	ds_read_b128 v[70:73], v31 offset:64
	s_waitcnt lgkmcnt(0)
	v_mfma_f32_16x16x32_bf16 v[24:27], v[82:85], v[70:73], v[24:27]
	s_nop 7
	v_pk_mul_f32 v[24:25], v[36:37], v[24:25]
	v_pk_mul_f32 v[26:27], v[40:41], v[26:27]
	v_cvt_pk_bf16_f32 v24, v24, v25
	v_cvt_pk_bf16_f32 v25, v26, v27
	ds_write_b64 v23, v[24:25] offset:46080
.LBB0_548:
	v_mul_u32_u24_e32 v22, 0x90, v22
	v_add_u32_e32 v22, 0, v22
	s_lshl_b32 s4, s4, 2
	v_and_or_b32 v21, s4, -16, v21
	v_add_u32_e32 v69, v22, v79
	s_waitcnt lgkmcnt(0)
	s_barrier
	ds_read_b128 v[22:25], v69 offset:27648
	v_mul_lo_u32 v26, v21, s61
	v_add_u32_e32 v76, 0, v26
	v_add_u32_e32 v110, 0x1200, v76
	v_add_u32_e32 v70, v76, v79
	v_add_u32_e32 v71, v110, v79
	ds_read_b128 v[72:75], v70 offset:46080
	ds_read_b128 v[82:85], v71 offset:46080
	s_waitcnt lgkmcnt(1)
	v_mfma_f32_16x16x32_bf16 v[72:75], v[22:25], v[72:75], 0
	ds_read_b128 v[86:89], v69 offset:36864
	ds_read_b128 v[90:93], v70 offset:27648
	ds_read_b128 v[98:101], v69 offset:27712
	v_mul_f32_e32 v94, 0, v28
	s_waitcnt lgkmcnt(3)
	v_mfma_f32_16x16x32_bf16 v[22:25], v[22:25], v[82:85], 0
	ds_read_b128 v[82:85], v71 offset:27648
	v_mov_b32_e32 v95, v94
	v_mov_b32_e32 v96, v94
	v_mov_b32_e32 v97, v94
	v_or_b32_e32 v20, s12, v20
	v_lshlrev_b32_e32 v111, 1, v20
	s_waitcnt lgkmcnt(2)
	v_mfma_f32_16x16x32_bf16 v[90:93], v[86:89], v[90:93], v[94:97]
	s_and_b64 s[12:13], s[8:9], exec
	s_cselect_b32 s4, 0xc0, 63
	s_or_b32 s2, s4, s2
	s_waitcnt lgkmcnt(0)
	v_mfma_f32_16x16x32_bf16 v[82:85], v[86:89], v[82:85], v[94:97]
	ds_read_b128 v[86:89], v70 offset:46144
	s_nop 1
	ds_read_b128 v[94:97], v69 offset:36928
	ds_read_b128 v[102:105], v71 offset:46144
	s_and_b64 s[12:13], s[8:9], exec
	s_cselect_b32 s4, s92, 0x1b485000
	s_waitcnt lgkmcnt(2)
	v_mfma_f32_16x16x32_bf16 v[86:89], v[98:101], v[86:89], v[72:75]
	s_nop 2
	ds_read_b128 v[72:75], v70 offset:27712
	ds_read_b128 v[106:109], v71 offset:27712
	s_add_u32 s12, s78, s4
	s_addc_u32 s13, s79, 0
	s_waitcnt lgkmcnt(2)
	v_mfma_f32_16x16x32_bf16 v[98:101], v[98:101], v[102:105], v[22:25]
	ds_read_b128 v[102:105], v69 offset:55296
	v_mov_b32_e32 v31, v30
	s_andn2_b64 vcc, exec, s[6:7]
	s_waitcnt lgkmcnt(2)
	v_mfma_f32_16x16x32_bf16 v[24:27], v[94:97], v[72:75], v[90:93]
	v_mul_lo_u32 v72, v21, s19
	v_or_b32_e32 v73, s0, v20
	v_add_u32_e32 v75, v76, v111
	ds_read_b128 v[90:93], v70 offset:18432
	s_waitcnt lgkmcnt(2)
	v_mfma_f32_16x16x32_bf16 v[20:23], v[94:97], v[106:109], v[82:85]
	s_nop 2
	ds_read_b128 v[82:85], v69 offset:55360
	ds_read_b128 v[94:97], v70 offset:18496
	ds_read_b128 v[106:109], v71 offset:18432
	v_cvt_pk_bf16_f32 v58, v24, v25
	v_cvt_pk_bf16_f32 v59, v26, v27
	s_waitcnt lgkmcnt(3)
	v_mfma_f32_16x16x32_bf16 v[86:89], v[102:105], v[90:93], v[86:89]
	ds_read_b128 v[90:93], v71 offset:18496
	ds_write_b64 v75, v[58:59] offset:64512
	v_cvt_pk_bf16_f32 v58, v20, v21
	s_waitcnt lgkmcnt(2)
	v_mfma_f32_16x16x32_bf16 v[98:101], v[102:105], v[106:109], v[98:101]
	v_cvt_pk_bf16_f32 v59, v22, v23
	v_add_u32_e32 v76, v110, v111
	v_lshl_add_u32 v74, s19, 5, v72
	v_mfma_f32_16x16x32_bf16 v[86:89], v[82:85], v[94:97], v[86:89]
	ds_write_b64 v76, v[58:59] offset:64512
	s_waitcnt lgkmcnt(2)
	v_mfma_f32_16x16x32_bf16 v[82:85], v[82:85], v[90:93], v[98:101]
	v_add_u32_e32 v90, s5, v72
	v_lshl_or_b32 v180, v90, 10, v73
	s_nop 2
	v_cvt_pk_bf16_f32 v58, v86, v87
	v_cvt_pk_bf16_f32 v59, v88, v89
	v_lshl_add_u64 v[86:87], v[180:181], 1, s[12:13]
	global_store_dwordx2 v[86:87], v[58:59], off offset:512
	v_add_u32_e32 v86, s5, v74
	v_lshl_or_b32 v180, v86, 10, v73
	v_cvt_pk_bf16_f32 v58, v82, v83
	v_cvt_pk_bf16_f32 v59, v84, v85
	v_lshl_add_u64 v[82:83], v[180:181], 1, s[12:13]
	global_store_dwordx2 v[82:83], v[58:59], off offset:512
	s_waitcnt lgkmcnt(0)
	s_barrier
	s_waitcnt vmcnt(13)
	ds_write_b128 v62, v[12:15]
	s_waitcnt vmcnt(12)
	ds_write_b128 v62, v[16:19] offset:9216
	v_lshlrev_b32_e32 v16, 16, v12
	v_and_b32_e32 v17, 0xffff0000, v12
	v_pk_mul_f32 v[16:17], v[30:31], v[16:17]
	s_mov_b64 s[4:5], -1
	v_cvt_pk_bf16_f32 v12, v16, v17
	v_lshlrev_b32_e32 v16, 16, v13
	v_and_b32_e32 v17, 0xffff0000, v13
	v_pk_mul_f32 v[16:17], v[30:31], v[16:17]
	s_nop 0
	v_cvt_pk_bf16_f32 v13, v16, v17
	v_lshlrev_b32_e32 v16, 16, v14
	v_and_b32_e32 v17, 0xffff0000, v14
	v_pk_mul_f32 v[16:17], v[30:31], v[16:17]
	s_nop 0
	v_cvt_pk_bf16_f32 v14, v16, v17
	v_lshlrev_b32_e32 v16, 16, v15
	v_and_b32_e32 v17, 0xffff0000, v15
	v_pk_mul_f32 v[16:17], v[30:31], v[16:17]
	s_nop 0
	v_cvt_pk_bf16_f32 v15, v16, v17
	ds_write_b128 v62, v[12:15] offset:18432
	s_waitcnt vmcnt(11)
	v_and_b32_e32 v12, 0xffff, v42
	s_waitcnt vmcnt(10)
	v_lshl_or_b32 v14, v52, 16, v12
	s_waitcnt vmcnt(9)
	v_lshlrev_b32_e32 v13, 16, v56
	s_waitcnt vmcnt(8)
	v_lshlrev_b32_e32 v12, 16, v54
	v_pk_mul_f32 v[12:13], v[32:33], v[12:13]
	s_nop 0
	v_cvt_pk_bf16_f32 v15, v12, v13
	v_lshrrev_b32_e32 v12, 16, v42
	v_and_or_b32 v12, v52, s60, v12
	ds_write2_b32 v63, v14, v12 offset1:36
	v_and_b32_e32 v13, 0xffff0000, v56
	v_and_b32_e32 v12, 0xffff0000, v54
	v_pk_mul_f32 v[12:13], v[32:33], v[12:13]
	v_add_u32_e32 v42, s2, v67
	v_cvt_pk_bf16_f32 v12, v12, v13
	ds_write2_b32 v64, v15, v12 offset1:36
	v_and_b32_e32 v12, 0xffff, v43
	v_lshl_or_b32 v14, v53, 16, v12
	v_lshlrev_b32_e32 v13, 16, v57
	v_lshlrev_b32_e32 v12, 16, v55
	v_pk_mul_f32 v[12:13], v[32:33], v[12:13]
	v_mad_u32_u24 v42, v42, s63, v61
	v_cvt_pk_bf16_f32 v15, v12, v13
	v_lshrrev_b32_e32 v12, 16, v43
	v_and_or_b32 v12, v53, s60, v12
	ds_write2_b32 v63, v14, v12 offset0:72 offset1:108
	v_and_b32_e32 v13, 0xffff0000, v57
	v_and_b32_e32 v12, 0xffff0000, v55
	v_pk_mul_f32 v[12:13], v[32:33], v[12:13]
	v_ashrrev_i32_e32 v43, 31, v42
	v_cvt_pk_bf16_f32 v12, v12, v13
	ds_write2_b32 v64, v15, v12 offset0:72 offset1:108
	v_add_u32_e32 v12, s2, v60
	v_mul_u32_u24_e32 v12, 0xe00, v12
	v_or3_b32 v12, v12, v77, s0
	v_ashrrev_i32_e32 v13, 31, v12
	v_lshl_add_u64 v[42:43], v[42:43], 1, s[82:83]
	v_lshl_add_u64 v[16:17], v[12:13], 1, s[82:83]
	v_lshl_add_u64 v[52:53], s[10:11], 1, v[42:43]
	s_waitcnt lgkmcnt(0)
	s_barrier
	global_load_dwordx4 v[12:15], v[16:17], off offset:2560 nt
	s_nop 0
	global_load_dwordx4 v[16:19], v[16:17], off offset:3072 nt
	s_nop 0
	global_load_dwordx2 v[56:57], v[42:43], off offset:3584 nt
	global_load_dwordx2 v[58:59], v[52:53], off offset:3584 nt
	global_load_dwordx2 v[54:55], v[52:53], off offset:3072 nt
	s_nop 0
	global_load_dwordx2 v[52:53], v[42:43], off offset:3072 nt
	ds_read_b128 v[82:85], v65 offset:9216
	ds_read_b128 v[86:89], v66
	ds_read_b128 v[90:93], v65 offset:9280
	s_waitcnt lgkmcnt(1)
	v_mfma_f32_16x16x32_bf16 v[82:85], v[82:85], v[86:89], 0
	ds_read_b128 v[86:89], v66 offset:64
	s_waitcnt lgkmcnt(0)
	v_mfma_f32_16x16x32_bf16 v[82:85], v[90:93], v[86:89], v[82:85]
	s_nop 7
	v_pk_mul_f32 v[42:43], v[34:35], v[82:83]
	v_pk_mul_f32 v[82:83], v[38:39], v[84:85]
	v_cvt_pk_bf16_f32 v42, v42, v43
	v_cvt_pk_bf16_f32 v43, v82, v83
	ds_write_b64 v68, v[42:43] offset:46080
	s_cbranch_vccnz .LBB0_550
	s_lshl_b32 s6, s18, 5
	v_mul_u32_u24_e32 v82, 0x90, v81
	s_mov_b64 s[4:5], 0
	v_mov_b32_e32 v83, s6

.LBB0_552:
	s_waitcnt lgkmcnt(0)
	s_barrier
	ds_read_b128 v[84:87], v69 offset:27648
	ds_read_b128 v[88:91], v70 offset:46080
	ds_read_b128 v[92:95], v69 offset:36864
	ds_read_b128 v[96:99], v71 offset:46080
	s_waitcnt lgkmcnt(2)
	v_mfma_f32_16x16x32_bf16 v[88:91], v[84:87], v[88:91], 0
	ds_read_b128 v[100:103], v70 offset:27648
	ds_read_b128 v[104:107], v71 offset:27648
	v_mov_b32_e32 v42, v28
	v_mov_b32_e32 v43, v28
	s_waitcnt lgkmcnt(2)
	v_mfma_f32_16x16x32_bf16 v[84:87], v[84:87], v[96:99], 0
	ds_read_b128 v[96:99], v69 offset:27712
	v_mov_b32_e32 v29, v28
	v_pk_mul_f32 v[26:27], v[28:29], v[26:27]
	v_pk_mul_f32 v[24:25], v[42:43], v[24:25]
	v_pk_mul_f32 v[22:23], v[28:29], v[22:23]
	v_pk_mul_f32 v[20:21], v[42:43], v[20:21]
	s_waitcnt lgkmcnt(2)
	v_mfma_f32_16x16x32_bf16 v[24:27], v[92:95], v[100:103], v[24:27]
	v_add_u32_e32 v81, s17, v72
	v_lshl_or_b32 v180, v81, 10, v73
	v_add_u32_e32 v81, s17, v74
	s_waitcnt lgkmcnt(1)
	v_mfma_f32_16x16x32_bf16 v[20:23], v[92:95], v[104:107], v[20:23]
	ds_read_b128 v[92:95], v70 offset:46144
	ds_read_b128 v[100:103], v71 offset:46144
	s_lshl_b32 s1, s1, 12
	s_bitset1_b32 s1, 11
	s_waitcnt lgkmcnt(1)
	v_mfma_f32_16x16x32_bf16 v[88:91], v[96:99], v[92:95], v[88:91]
	ds_read_b128 v[92:95], v69 offset:36928
	s_and_b64 s[4:5], s[8:9], exec
	s_cselect_b32 s4, 0, 0xfff
	s_waitcnt lgkmcnt(1)
	v_mfma_f32_16x16x32_bf16 v[84:87], v[96:99], v[100:103], v[84:87]
	ds_read_b128 v[96:99], v70 offset:27712
	ds_read_b128 v[100:103], v71 offset:27712
	s_add_i32 s4, s1, s4
	s_andn2_b64 vcc, exec, s[14:15]
	s_waitcnt lgkmcnt(1)
	v_mfma_f32_16x16x32_bf16 v[24:27], v[92:95], v[96:99], v[24:27]
	ds_read_b128 v[96:99], v69 offset:64512
	s_waitcnt lgkmcnt(1)
	v_mfma_f32_16x16x32_bf16 v[20:23], v[92:95], v[100:103], v[20:23]
	ds_read_b128 v[92:95], v70 offset:18432
	ds_read_b128 v[100:103], v69 offset:64576
	ds_read_b128 v[104:107], v71 offset:18432
	ds_read_b128 v[108:111], v71 offset:18496
	s_waitcnt lgkmcnt(3)
	v_mfma_f32_16x16x32_bf16 v[88:91], v[96:99], v[92:95], v[88:91]
	ds_read_b128 v[92:95], v70 offset:18496
	s_waitcnt lgkmcnt(2)
	v_mfma_f32_16x16x32_bf16 v[84:87], v[96:99], v[104:107], v[84:87]
	v_cvt_pk_bf16_f32 v96, v24, v25
	v_cvt_pk_bf16_f32 v97, v26, v27
	ds_write_b64 v75, v[96:97] offset:55296
	s_waitcnt lgkmcnt(1)
	v_mfma_f32_16x16x32_bf16 v[88:91], v[100:103], v[92:95], v[88:91]
	v_cvt_pk_bf16_f32 v92, v20, v21
	v_cvt_pk_bf16_f32 v93, v22, v23
	ds_write_b64 v76, v[92:93] offset:55296
	v_mfma_f32_16x16x32_bf16 v[84:87], v[100:103], v[108:111], v[84:87]
	s_nop 3
	v_cvt_pk_bf16_f32 v88, v88, v89
	v_cvt_pk_bf16_f32 v89, v90, v91
	v_lshl_add_u64 v[90:91], v[180:181], 1, s[12:13]
	v_lshl_or_b32 v180, v81, 10, v73
	v_cvt_pk_bf16_f32 v84, v84, v85
	v_cvt_pk_bf16_f32 v85, v86, v87
	v_lshl_add_u64 v[86:87], v[180:181], 1, s[12:13]
	global_store_dwordx2 v[90:91], v[88:89], off offset:512
	global_store_dwordx2 v[86:87], v[84:85], off offset:512
	s_waitcnt lgkmcnt(0)
	s_barrier
	s_waitcnt vmcnt(15)
	ds_write_b128 v62, v[4:7]
	s_waitcnt vmcnt(14)
	ds_write_b128 v62, v[8:11] offset:9216
	v_lshlrev_b32_e32 v8, 16, v4
	v_and_b32_e32 v9, 0xffff0000, v4
	v_pk_mul_f32 v[8:9], v[30:31], v[8:9]
	s_nop 0
	v_cvt_pk_bf16_f32 v4, v8, v9
	v_lshlrev_b32_e32 v8, 16, v5
	v_and_b32_e32 v9, 0xffff0000, v5
	v_pk_mul_f32 v[8:9], v[30:31], v[8:9]
	s_nop 0
	v_cvt_pk_bf16_f32 v5, v8, v9
	v_lshlrev_b32_e32 v8, 16, v6
	v_and_b32_e32 v9, 0xffff0000, v6
	v_pk_mul_f32 v[8:9], v[30:31], v[8:9]
	s_nop 0
	v_cvt_pk_bf16_f32 v6, v8, v9
	v_lshlrev_b32_e32 v8, 16, v7
	v_and_b32_e32 v9, 0xffff0000, v7
	v_pk_mul_f32 v[8:9], v[30:31], v[8:9]
	s_nop 0
	v_cvt_pk_bf16_f32 v7, v8, v9
	ds_write_b128 v62, v[4:7] offset:18432
	s_waitcnt vmcnt(13)
	v_and_b32_e32 v4, 0xffff, v44
	s_waitcnt vmcnt(12)
	v_lshl_or_b32 v6, v46, 16, v4
	s_waitcnt vmcnt(11)
	v_lshlrev_b32_e32 v5, 16, v50
	s_waitcnt vmcnt(10)
	v_lshlrev_b32_e32 v4, 16, v48
	v_pk_mul_f32 v[4:5], v[32:33], v[4:5]
	s_nop 0
	v_cvt_pk_bf16_f32 v7, v4, v5
	v_lshrrev_b32_e32 v4, 16, v44
	v_and_or_b32 v4, v46, s60, v4
	ds_write2_b32 v63, v6, v4 offset1:36
	v_and_b32_e32 v5, 0xffff0000, v50
	v_and_b32_e32 v4, 0xffff0000, v48
	v_pk_mul_f32 v[4:5], v[32:33], v[4:5]
	v_add_u32_e32 v44, s4, v67
	v_cvt_pk_bf16_f32 v4, v4, v5
	ds_write2_b32 v64, v7, v4 offset1:36
	v_and_b32_e32 v4, 0xffff, v45
	v_lshl_or_b32 v6, v47, 16, v4
	v_lshlrev_b32_e32 v5, 16, v51
	v_lshlrev_b32_e32 v4, 16, v49
	v_pk_mul_f32 v[4:5], v[32:33], v[4:5]
	v_mad_u32_u24 v44, v44, s63, v61
	v_cvt_pk_bf16_f32 v7, v4, v5
	v_lshrrev_b32_e32 v4, 16, v45
	v_and_or_b32 v4, v47, s60, v4
	ds_write2_b32 v63, v6, v4 offset0:72 offset1:108
	v_and_b32_e32 v5, 0xffff0000, v51
	v_and_b32_e32 v4, 0xffff0000, v49
	v_pk_mul_f32 v[4:5], v[32:33], v[4:5]
	v_ashrrev_i32_e32 v45, 31, v44
	v_cvt_pk_bf16_f32 v4, v4, v5
	ds_write2_b32 v64, v7, v4 offset0:72 offset1:108
	v_add_u32_e32 v4, s4, v60
	v_mul_u32_u24_e32 v4, 0xe00, v4
	v_or3_b32 v4, v4, v77, s0
	v_ashrrev_i32_e32 v5, 31, v4
	v_lshl_add_u64 v[50:51], v[44:45], 1, s[82:83]
	v_lshl_add_u64 v[8:9], v[4:5], 1, s[82:83]
	v_lshl_add_u64 v[48:49], s[10:11], 1, v[50:51]
	s_waitcnt lgkmcnt(0)
	s_barrier
	global_load_dwordx4 v[4:7], v[8:9], off offset:2560 nt
	s_nop 0
	global_load_dwordx4 v[8:11], v[8:9], off offset:3072 nt
	s_nop 0
	global_load_dwordx2 v[44:45], v[50:51], off offset:3584 nt
	global_load_dwordx2 v[46:47], v[48:49], off offset:3584 nt
	s_nop 0
	global_load_dwordx2 v[48:49], v[48:49], off offset:3072 nt
	s_nop 0
	global_load_dwordx2 v[50:51], v[50:51], off offset:3072 nt
	ds_read_b128 v[84:87], v65 offset:9216
	ds_read_b128 v[88:91], v65 offset:9280
	ds_read_b128 v[92:95], v66
	ds_read_b128 v[96:99], v66 offset:64
	s_waitcnt lgkmcnt(1)
	v_mfma_f32_16x16x32_bf16 v[84:87], v[84:87], v[92:95], 0
	v_add_u32_e32 v92, 0, v80
	v_add_u32_e32 v93, 0, v82
	v_add_u32_e32 v82, v78, v82
	s_waitcnt lgkmcnt(0)
	v_mfma_f32_16x16x32_bf16 v[84:87], v[88:91], v[96:99], v[84:87]
	v_cndmask_b32_e64 v78, 0, 1, s[14:15]
	v_cmp_ne_u32_e64 s[6:7], 1, v78
	v_add_u32_e32 v78, v92, v79
	v_add_u32_e32 v79, v93, v79
	s_nop 3
	v_pk_mul_f32 v[80:81], v[34:35], v[84:85]
	v_pk_mul_f32 v[84:85], v[38:39], v[86:87]
	v_cvt_pk_bf16_f32 v80, v80, v81
	v_cvt_pk_bf16_f32 v81, v84, v85
	ds_write_b64 v68, v[80:81] offset:46080
	v_add_u32_e32 v80, v82, v83
	s_cbranch_vccnz .LBB0_554
	ds_read_b128 v[82:85], v78 offset:9216
	ds_read_b128 v[86:89], v79
	ds_read_b128 v[90:93], v78 offset:9280
	s_waitcnt lgkmcnt(1)
	v_mfma_f32_16x16x32_bf16 v[82:85], v[82:85], v[86:89], 0
	ds_read_b128 v[86:89], v79 offset:64
	s_waitcnt lgkmcnt(0)
	v_mfma_f32_16x16x32_bf16 v[82:85], v[90:93], v[86:89], v[82:85]
	s_nop 7
	v_pk_mul_f32 v[82:83], v[36:37], v[82:83]
	v_pk_mul_f32 v[84:85], v[40:41], v[84:85]
	v_cvt_pk_bf16_f32 v82, v82, v83
	v_cvt_pk_bf16_f32 v83, v84, v85
	ds_write_b64 v80, v[82:83] offset:46080
.LBB0_554:
	s_waitcnt lgkmcnt(0)
	s_barrier
	ds_read_b128 v[82:85], v69 offset:27648
	ds_read_b128 v[86:89], v70 offset:46080
	ds_read_b128 v[90:93], v69 offset:36864
	ds_read_b128 v[94:97], v71 offset:46080
	ds_read_b128 v[98:101], v70 offset:27648
	v_pk_mul_f32 v[26:27], v[28:29], v[26:27]
	v_pk_mul_f32 v[24:25], v[42:43], v[24:25]
	s_waitcnt lgkmcnt(3)
	v_mfma_f32_16x16x32_bf16 v[86:89], v[82:85], v[86:89], 0
	v_mul_f32_e64 v22, v28, v22
	v_mul_f32_e64 v23, v29, v23
	v_pk_mul_f32 v[20:21], v[42:43], v[20:21]
	v_add_u32_e32 v29, s16, v72
	s_waitcnt lgkmcnt(1)
	v_mfma_f32_16x16x32_bf16 v[82:85], v[82:85], v[94:97], 0
	ds_read_b128 v[94:97], v71 offset:27648
	v_lshl_or_b32 v180, v29, 10, v73
	v_add_u32_e32 v29, s16, v74
	s_waitcnt lgkmcnt(1)
	v_mfma_f32_16x16x32_bf16 v[24:27], v[90:93], v[98:101], v[24:27]
	ds_read_b128 v[98:101], v69 offset:27712
	s_and_b64 s[4:5], s[8:9], exec
	s_cselect_b32 s4, 64, 0xfbf
	s_waitcnt lgkmcnt(1)
	v_mfma_f32_16x16x32_bf16 v[20:23], v[90:93], v[94:97], v[20:23]
	ds_read_b128 v[90:93], v70 offset:46144
	ds_read_b128 v[94:97], v71 offset:46144
	s_add_i32 s4, s1, s4
	s_and_b64 vcc, exec, s[6:7]
	s_waitcnt lgkmcnt(1)
	v_mfma_f32_16x16x32_bf16 v[86:89], v[98:101], v[90:93], v[86:89]
	ds_read_b128 v[90:93], v69 offset:36928
	s_waitcnt lgkmcnt(1)
	v_mfma_f32_16x16x32_bf16 v[82:85], v[98:101], v[94:97], v[82:85]
	ds_read_b128 v[94:97], v70 offset:27712
	ds_read_b128 v[98:101], v71 offset:27712
	ds_read_b128 v[102:105], v69 offset:55296
	s_waitcnt lgkmcnt(2)
	v_mfma_f32_16x16x32_bf16 v[24:27], v[90:93], v[94:97], v[24:27]
	ds_read_b128 v[94:97], v69 offset:55360
	ds_read_b128 v[106:109], v70 offset:18432
	ds_read_b128 v[110:113], v70 offset:18496
	s_nop 4
	v_cvt_pk_bf16_f32 v114, v24, v25
	s_waitcnt lgkmcnt(4)
	v_mfma_f32_16x16x32_bf16 v[20:23], v[90:93], v[98:101], v[20:23]
	ds_read_b128 v[90:93], v71 offset:18432
	ds_read_b128 v[98:101], v71 offset:18496
	v_cvt_pk_bf16_f32 v115, v26, v27
	ds_write_b64 v75, v[114:115] offset:64512
	s_waitcnt lgkmcnt(4)
	v_mfma_f32_16x16x32_bf16 v[86:89], v[102:105], v[106:109], v[86:89]
	s_nop 1
	v_cvt_pk_bf16_f32 v106, v20, v21
	v_cvt_pk_bf16_f32 v107, v22, v23
	ds_write_b64 v76, v[106:107] offset:64512
	s_waitcnt lgkmcnt(3)
	v_mfma_f32_16x16x32_bf16 v[82:85], v[102:105], v[90:93], v[82:85]
	v_mfma_f32_16x16x32_bf16 v[86:89], v[94:97], v[110:113], v[86:89]
	s_waitcnt lgkmcnt(2)
	v_mfma_f32_16x16x32_bf16 v[82:85], v[94:97], v[98:101], v[82:85]
	s_nop 5
	v_cvt_pk_bf16_f32 v86, v86, v87
	v_cvt_pk_bf16_f32 v87, v88, v89
	v_lshl_add_u64 v[88:89], v[180:181], 1, s[12:13]
	v_lshl_or_b32 v180, v29, 10, v73
	v_cvt_pk_bf16_f32 v82, v82, v83
	v_cvt_pk_bf16_f32 v83, v84, v85
	v_lshl_add_u64 v[84:85], v[180:181], 1, s[12:13]
	global_store_dwordx2 v[88:89], v[86:87], off offset:512
	global_store_dwordx2 v[84:85], v[82:83], off offset:512
	s_waitcnt lgkmcnt(0)
	s_barrier
	s_waitcnt vmcnt(15)
	ds_write_b128 v62, v[12:15]
	s_waitcnt vmcnt(14)
	ds_write_b128 v62, v[16:19] offset:9216
	v_lshlrev_b32_e32 v16, 16, v12
	v_and_b32_e32 v17, 0xffff0000, v12
	v_pk_mul_f32 v[16:17], v[30:31], v[16:17]
	v_add_u32_e32 v29, s4, v67
	v_cvt_pk_bf16_f32 v12, v16, v17
	v_lshlrev_b32_e32 v16, 16, v13
	v_and_b32_e32 v17, 0xffff0000, v13
	v_pk_mul_f32 v[16:17], v[30:31], v[16:17]
	s_nop 0
	v_cvt_pk_bf16_f32 v13, v16, v17
	v_lshlrev_b32_e32 v16, 16, v14
	v_and_b32_e32 v17, 0xffff0000, v14
	v_pk_mul_f32 v[16:17], v[30:31], v[16:17]
	s_nop 0
	v_cvt_pk_bf16_f32 v14, v16, v17
	v_lshlrev_b32_e32 v16, 16, v15
	v_and_b32_e32 v17, 0xffff0000, v15
	v_pk_mul_f32 v[16:17], v[30:31], v[16:17]
	s_nop 0
	v_cvt_pk_bf16_f32 v15, v16, v17
	ds_write_b128 v62, v[12:15] offset:18432
	s_waitcnt vmcnt(13)
	v_and_b32_e32 v12, 0xffff, v56
	s_waitcnt vmcnt(12)
	v_lshl_or_b32 v14, v58, 16, v12
	s_waitcnt vmcnt(11)
	v_lshlrev_b32_e32 v13, 16, v54
	s_waitcnt vmcnt(10)
	v_lshlrev_b32_e32 v12, 16, v52
	v_pk_mul_f32 v[12:13], v[32:33], v[12:13]
	s_nop 0
	v_cvt_pk_bf16_f32 v15, v12, v13
	v_lshrrev_b32_e32 v12, 16, v56
	v_and_or_b32 v12, v58, s60, v12
	ds_write2_b32 v63, v14, v12 offset1:36
	v_and_b32_e32 v13, 0xffff0000, v54
	v_and_b32_e32 v12, 0xffff0000, v52
	v_pk_mul_f32 v[12:13], v[32:33], v[12:13]
	v_mad_u32_u24 v52, v29, s63, v61
	v_cvt_pk_bf16_f32 v12, v12, v13
	ds_write2_b32 v64, v15, v12 offset1:36
	v_and_b32_e32 v12, 0xffff, v57
	v_lshl_or_b32 v14, v59, 16, v12
	v_lshlrev_b32_e32 v13, 16, v55
	v_lshlrev_b32_e32 v12, 16, v53
	v_pk_mul_f32 v[12:13], v[32:33], v[12:13]
	s_nop 0
	v_cvt_pk_bf16_f32 v15, v12, v13
	v_lshrrev_b32_e32 v12, 16, v57
	v_and_or_b32 v12, v59, s60, v12
	ds_write2_b32 v63, v14, v12 offset0:72 offset1:108
	v_and_b32_e32 v13, 0xffff0000, v55
	v_and_b32_e32 v12, 0xffff0000, v53
	v_pk_mul_f32 v[12:13], v[32:33], v[12:13]
	v_ashrrev_i32_e32 v53, 31, v52
	v_cvt_pk_bf16_f32 v12, v12, v13
	ds_write2_b32 v64, v15, v12 offset0:72 offset1:108
	v_add_u32_e32 v12, s4, v60
	v_mul_u32_u24_e32 v12, 0xe00, v12
	v_or3_b32 v12, v12, v77, s0
	v_ashrrev_i32_e32 v13, 31, v12
	v_lshl_add_u64 v[58:59], v[52:53], 1, s[82:83]
	v_lshl_add_u64 v[16:17], v[12:13], 1, s[82:83]
	v_lshl_add_u64 v[56:57], s[10:11], 1, v[58:59]
	s_waitcnt lgkmcnt(0)
	s_barrier
	global_load_dwordx4 v[12:15], v[16:17], off offset:2560 nt
	s_nop 0
	global_load_dwordx4 v[16:19], v[16:17], off offset:3072 nt
	s_nop 0
	global_load_dwordx2 v[52:53], v[58:59], off offset:3584 nt
	global_load_dwordx2 v[54:55], v[56:57], off offset:3584 nt
	s_nop 0
	global_load_dwordx2 v[56:57], v[56:57], off offset:3072 nt
	s_nop 0
	global_load_dwordx2 v[58:59], v[58:59], off offset:3072 nt
	ds_read_b128 v[82:85], v65 offset:9216
	ds_read_b128 v[86:89], v66
	ds_read_b128 v[90:93], v65 offset:9280
	s_waitcnt lgkmcnt(1)
	v_mfma_f32_16x16x32_bf16 v[82:85], v[82:85], v[86:89], 0
	ds_read_b128 v[86:89], v66 offset:64
	s_waitcnt lgkmcnt(0)
	v_mfma_f32_16x16x32_bf16 v[82:85], v[90:93], v[86:89], v[82:85]
	s_nop 7
	v_pk_mul_f32 v[82:83], v[34:35], v[82:83]
	v_pk_mul_f32 v[84:85], v[38:39], v[84:85]
	v_cvt_pk_bf16_f32 v82, v82, v83
	v_cvt_pk_bf16_f32 v83, v84, v85
	ds_write_b64 v68, v[82:83] offset:46080
	s_cbranch_vccnz .LBB0_556
	ds_read_b128 v[82:85], v78 offset:9216
	ds_read_b128 v[86:89], v79
	ds_read_b128 v[90:93], v78 offset:9280
	s_waitcnt lgkmcnt(1)
	v_mfma_f32_16x16x32_bf16 v[82:85], v[82:85], v[86:89], 0
	ds_read_b128 v[86:89], v79 offset:64
	s_waitcnt lgkmcnt(0)
	v_mfma_f32_16x16x32_bf16 v[82:85], v[90:93], v[86:89], v[82:85]
	s_nop 7
	v_pk_mul_f32 v[82:83], v[36:37], v[82:83]
	v_pk_mul_f32 v[84:85], v[40:41], v[84:85]
	v_cvt_pk_bf16_f32 v82, v82, v83
	v_cvt_pk_bf16_f32 v83, v84, v85
	ds_write_b64 v80, v[82:83] offset:46080

.LBB0_558:
	s_waitcnt vmcnt(15)
	v_lshlrev_b32_e32 v82, 16, v4
	v_and_b32_e32 v83, 0xffff0000, v4
	v_lshlrev_b32_e32 v84, 16, v5
	v_and_b32_e32 v85, 0xffff0000, v5
	v_pk_mul_f32 v[82:83], v[30:31], v[82:83]
	v_pk_mul_f32 v[84:85], v[30:31], v[84:85]
	v_cvt_pk_bf16_f32 v82, v82, v83
	v_cvt_pk_bf16_f32 v83, v84, v85
	v_lshlrev_b32_e32 v84, 16, v6
	v_and_b32_e32 v85, 0xffff0000, v6
	v_lshlrev_b32_e32 v86, 16, v7
	v_and_b32_e32 v87, 0xffff0000, v7
	v_pk_mul_f32 v[84:85], v[30:31], v[84:85]
	v_pk_mul_f32 v[86:87], v[30:31], v[86:87]
	v_cvt_pk_bf16_f32 v84, v84, v85
	v_cvt_pk_bf16_f32 v85, v86, v87
	ds_write_b128 v62, v[4:7]
	s_waitcnt vmcnt(14)
	ds_write_b128 v62, v[8:11] offset:9216
	ds_write_b128 v62, v[82:85] offset:18432
	s_waitcnt vmcnt(5)
	v_lshlrev_b32_e32 v83, 16, v48
	s_waitcnt vmcnt(4)
	v_lshlrev_b32_e32 v82, 16, v50
	v_pk_mul_f32 v[82:83], v[32:33], v[82:83]
	v_lshlrev_b32_e32 v29, 16, v46
	s_mov_b32 s5, 0xffff
	v_cvt_pk_bf16_f32 v81, v82, v83
	v_lshrrev_b32_e32 v82, 16, v44
	v_and_or_b32 v29, v44, s5, v29
	v_and_or_b32 v82, v46, s60, v82
	ds_write2_b32 v63, v29, v82 offset1:36
	v_and_b32_e32 v83, 0xffff0000, v48
	v_and_b32_e32 v82, 0xffff0000, v50
	v_pk_mul_f32 v[82:83], v[32:33], v[82:83]
	s_cmpk_lt_u32 s0, 0x42
	v_cvt_pk_bf16_f32 v29, v82, v83
	v_lshlrev_b32_e32 v83, 16, v49
	v_lshlrev_b32_e32 v82, 16, v51
	v_pk_mul_f32 v[82:83], v[32:33], v[82:83]
	ds_write2_b32 v64, v81, v29 offset1:36
	v_lshlrev_b32_e32 v29, 16, v47
	v_cvt_pk_bf16_f32 v81, v82, v83
	v_lshrrev_b32_e32 v82, 16, v45
	v_and_or_b32 v29, v45, s5, v29
	v_and_or_b32 v82, v47, s60, v82
	ds_write2_b32 v63, v29, v82 offset0:72 offset1:108
	v_and_b32_e32 v83, 0xffff0000, v49
	v_and_b32_e32 v82, 0xffff0000, v51
	s_cselect_b64 s[16:17], -1, 0
	s_cmpk_gt_u32 s0, 0x41
	v_pk_mul_f32 v[82:83], v[32:33], v[82:83]
	s_cselect_b64 s[14:15], -1, 0
	v_cvt_pk_bf16_f32 v29, v82, v83
	s_and_b64 vcc, exec, s[14:15]
	ds_write2_b32 v64, v81, v29 offset0:72 offset1:108
	s_waitcnt lgkmcnt(0)
	s_barrier
	s_cbranch_vccnz .LBB0_560
	s_add_i32 s5, s2, 0xffffff80
	s_and_b64 s[18:19], s[8:9], exec
	s_cselect_b32 s5, s4, s5
	s_add_i32 s5, s5, s1
	v_add_u32_e32 v4, s5, v60
	v_add_u32_e32 v29, s5, v67
	v_mul_u32_u24_e32 v4, 0xe00, v4
	v_mad_u32_u24 v44, v29, s63, v61
	v_or_b32_e32 v4, v4, v77
	v_ashrrev_i32_e32 v45, 31, v44
	v_ashrrev_i32_e32 v5, 31, v4
	v_lshl_add_u64 v[50:51], v[44:45], 1, s[82:83]
	v_lshl_add_u64 v[8:9], v[4:5], 1, s[82:83]
	v_lshl_add_u64 v[48:49], s[10:11], 1, v[50:51]
	global_load_dwordx4 v[4:7], v[8:9], off offset:2560 nt
	s_nop 0
	global_load_dwordx4 v[8:11], v[8:9], off offset:3072 nt
	s_nop 0
	global_load_dwordx2 v[44:45], v[50:51], off offset:3584 nt
	global_load_dwordx2 v[46:47], v[48:49], off offset:3584 nt
	s_nop 0
	global_load_dwordx2 v[48:49], v[48:49], off offset:3072 nt
	s_nop 0
	global_load_dwordx2 v[50:51], v[50:51], off offset:3072 nt

.LBB0_562:
	s_waitcnt lgkmcnt(0)
	s_barrier
	ds_read_b128 v[82:85], v69 offset:27648
	ds_read_b128 v[86:89], v70 offset:46080
	ds_read_b128 v[90:93], v69 offset:36864
	ds_read_b128 v[94:97], v71 offset:46080
	ds_read_b128 v[98:101], v70 offset:27648
	ds_read_b128 v[102:105], v71 offset:27648
	s_waitcnt lgkmcnt(4)
	v_mfma_f32_16x16x32_bf16 v[86:89], v[82:85], v[86:89], 0
	v_mov_b32_e32 v29, v28
	v_pk_mul_f32 v[26:27], v[28:29], v[26:27]
	v_pk_mul_f32 v[24:25], v[42:43], v[24:25]
	s_waitcnt lgkmcnt(2)
	v_mfma_f32_16x16x32_bf16 v[82:85], v[82:85], v[94:97], 0
	ds_read_b128 v[94:97], v69 offset:27712
	v_pk_mul_f32 v[22:23], v[28:29], v[22:23]
	v_pk_mul_f32 v[20:21], v[42:43], v[20:21]
	s_waitcnt lgkmcnt(2)
	v_mfma_f32_16x16x32_bf16 v[24:27], v[90:93], v[98:101], v[24:27]
	s_add_i32 s5, s4, 0xffffff80
	s_and_b64 s[18:19], s[8:9], exec
	s_cselect_b32 s5, s5, s2
	s_waitcnt lgkmcnt(1)
	v_mfma_f32_16x16x32_bf16 v[20:23], v[90:93], v[102:105], v[20:23]
	ds_read_b128 v[90:93], v70 offset:46144
	ds_read_b128 v[98:101], v71 offset:46144
	s_add_i32 s5, s5, s1
	v_add_u32_e32 v29, s5, v72
	s_waitcnt lgkmcnt(1)
	v_mfma_f32_16x16x32_bf16 v[86:89], v[94:97], v[90:93], v[86:89]
	ds_read_b128 v[90:93], v69 offset:36928
	v_lshl_or_b32 v180, v29, 10, v73
	v_add_u32_e32 v29, s5, v74
	s_waitcnt lgkmcnt(1)
	v_mfma_f32_16x16x32_bf16 v[82:85], v[94:97], v[98:101], v[82:85]
	ds_read_b128 v[94:97], v70 offset:27712
	ds_read_b128 v[98:101], v71 offset:27712
	ds_read_b128 v[102:105], v70 offset:18432
	s_mov_b32 s5, 0xffff
	s_waitcnt lgkmcnt(2)
	v_mfma_f32_16x16x32_bf16 v[24:27], v[90:93], v[94:97], v[24:27]
	ds_read_b128 v[94:97], v69 offset:55296
	s_andn2_b64 vcc, exec, s[16:17]
	s_waitcnt lgkmcnt(2)
	v_mfma_f32_16x16x32_bf16 v[20:23], v[90:93], v[98:101], v[20:23]
	ds_read_b128 v[90:93], v69 offset:55360
	ds_read_b128 v[98:101], v70 offset:18496
	ds_read_b128 v[106:109], v71 offset:18432
	s_waitcnt lgkmcnt(3)
	v_mfma_f32_16x16x32_bf16 v[86:89], v[94:97], v[102:105], v[86:89]
	ds_read_b128 v[102:105], v71 offset:18496
	s_waitcnt lgkmcnt(1)
	v_mfma_f32_16x16x32_bf16 v[82:85], v[94:97], v[106:109], v[82:85]
	v_cvt_pk_bf16_f32 v94, v24, v25
	v_cvt_pk_bf16_f32 v95, v26, v27
	ds_write_b64 v75, v[94:95] offset:64512
	v_mfma_f32_16x16x32_bf16 v[86:89], v[90:93], v[98:101], v[86:89]
	v_cvt_pk_bf16_f32 v94, v20, v21
	v_cvt_pk_bf16_f32 v95, v22, v23
	ds_write_b64 v76, v[94:95] offset:64512
	s_waitcnt lgkmcnt(2)
	v_mfma_f32_16x16x32_bf16 v[82:85], v[90:93], v[102:105], v[82:85]
	s_nop 2
	v_cvt_pk_bf16_f32 v86, v86, v87
	v_cvt_pk_bf16_f32 v87, v88, v89
	v_lshl_add_u64 v[88:89], v[180:181], 1, s[12:13]
	v_lshl_or_b32 v180, v29, 10, v73
	s_nop 0
	v_cvt_pk_bf16_f32 v82, v82, v83
	v_cvt_pk_bf16_f32 v83, v84, v85
	v_lshl_add_u64 v[84:85], v[180:181], 1, s[12:13]
	global_store_dwordx2 v[88:89], v[86:87], off offset:512
	global_store_dwordx2 v[84:85], v[82:83], off offset:512
	s_waitcnt vmcnt(9)
	v_lshlrev_b32_e32 v82, 16, v12
	v_and_b32_e32 v83, 0xffff0000, v12
	v_lshlrev_b32_e32 v84, 16, v13
	v_and_b32_e32 v85, 0xffff0000, v13
	v_pk_mul_f32 v[82:83], v[30:31], v[82:83]
	v_pk_mul_f32 v[84:85], v[30:31], v[84:85]
	v_cvt_pk_bf16_f32 v82, v82, v83
	v_cvt_pk_bf16_f32 v83, v84, v85
	v_lshlrev_b32_e32 v84, 16, v14
	v_and_b32_e32 v85, 0xffff0000, v14
	v_lshlrev_b32_e32 v86, 16, v15
	v_and_b32_e32 v87, 0xffff0000, v15
	v_pk_mul_f32 v[84:85], v[30:31], v[84:85]
	v_pk_mul_f32 v[86:87], v[30:31], v[86:87]
	v_cvt_pk_bf16_f32 v84, v84, v85
	v_cvt_pk_bf16_f32 v85, v86, v87
	s_waitcnt lgkmcnt(0)
	s_barrier
	ds_write_b128 v62, v[12:15]
	s_waitcnt vmcnt(8)
	ds_write_b128 v62, v[16:19] offset:9216
	ds_write_b128 v62, v[82:85] offset:18432
	s_waitcnt vmcnt(5)
	v_lshlrev_b32_e32 v83, 16, v56
	s_waitcnt vmcnt(4)
	v_lshlrev_b32_e32 v82, 16, v58
	v_pk_mul_f32 v[82:83], v[32:33], v[82:83]
	v_lshlrev_b32_e32 v29, 16, v54
	v_cvt_pk_bf16_f32 v81, v82, v83
	v_lshrrev_b32_e32 v82, 16, v52
	v_and_or_b32 v29, v52, s5, v29
	v_and_or_b32 v82, v54, s60, v82
	ds_write2_b32 v63, v29, v82 offset1:36
	v_and_b32_e32 v83, 0xffff0000, v56
	v_and_b32_e32 v82, 0xffff0000, v58
	v_pk_mul_f32 v[82:83], v[32:33], v[82:83]
	s_nop 0
	v_cvt_pk_bf16_f32 v29, v82, v83
	v_lshlrev_b32_e32 v83, 16, v57
	v_lshlrev_b32_e32 v82, 16, v59
	v_pk_mul_f32 v[82:83], v[32:33], v[82:83]
	ds_write2_b32 v64, v81, v29 offset1:36
	v_lshlrev_b32_e32 v29, 16, v55
	v_cvt_pk_bf16_f32 v81, v82, v83
	v_lshrrev_b32_e32 v82, 16, v53
	v_and_or_b32 v29, v53, s5, v29
	v_and_or_b32 v82, v55, s60, v82
	ds_write2_b32 v63, v29, v82 offset0:72 offset1:108
	v_and_b32_e32 v83, 0xffff0000, v57
	v_and_b32_e32 v82, 0xffff0000, v59
	v_pk_mul_f32 v[82:83], v[32:33], v[82:83]
	s_nop 0
	v_cvt_pk_bf16_f32 v29, v82, v83
	ds_write2_b32 v64, v81, v29 offset0:72 offset1:108
	s_waitcnt lgkmcnt(0)
	s_barrier
	s_cbranch_vccnz .LBB0_564
	s_add_i32 s5, s4, 64
	s_add_i32 s18, s2, 0xffffff40
	s_and_b64 s[16:17], s[8:9], exec
	s_cselect_b32 s5, s5, s18
	s_add_i32 s5, s5, s1
	v_add_u32_e32 v12, s5, v60
	v_add_u32_e32 v29, s5, v67
	v_mul_u32_u24_e32 v12, 0xe00, v12
	v_mad_u32_u24 v52, v29, s63, v61
	v_or_b32_e32 v12, v12, v77
	v_ashrrev_i32_e32 v53, 31, v52
	v_ashrrev_i32_e32 v13, 31, v12
	v_lshl_add_u64 v[58:59], v[52:53], 1, s[82:83]
	v_lshl_add_u64 v[16:17], v[12:13], 1, s[82:83]
	v_lshl_add_u64 v[56:57], s[10:11], 1, v[58:59]
	global_load_dwordx4 v[12:15], v[16:17], off offset:2560 nt
	s_nop 0
	global_load_dwordx4 v[16:19], v[16:17], off offset:3072 nt
	s_nop 0
	global_load_dwordx2 v[52:53], v[58:59], off offset:3584 nt
	global_load_dwordx2 v[54:55], v[56:57], off offset:3584 nt
	s_nop 0
	global_load_dwordx2 v[56:57], v[56:57], off offset:3072 nt
	s_nop 0
	global_load_dwordx2 v[58:59], v[58:59], off offset:3072 nt
